# GEMM k-loops: the clamped (duplicate) prefetch of the last loop trip is skipped so the tail drain waits only for the last real k-slice
# baseline (speedup 1.0000x reference)
; template <int NT, bool BKN, bool MASK = false, bool ROWSS = false, class Epi> ...
;     ...
;   float ss_[4] = {0.f, 0.f, 0.f, 0.f};
;   int stk_ = 0;
;   f32x4 acc[4][NT];
; #pragma unroll
;   for (int i = 0; i < 4; ++i)
; #pragma unroll
;     for (int j = 0; j < NT; ++j) acc[i][j] = (f32x4){0.f, 0.f, 0.f, 0.f};
;   const int nk = K >> 6;
;   const int nkm1 = nk - 1;
;   __syncthreads();
;   GEMM_LOAD(ra0, rb0, 0);
;   GEMM_LOAD(ra1, rb1, 1);
;   GEMM_STORE(ra0, rb0, 0);
;   GEMM_LOAD(ra0, rb0, (2 < nkm1 ? 2 : nkm1));
;   __syncthreads();
;   for (int kt = 0; kt < nk - 2; kt += 2) {
;     GEMM_COMPUTE(0);
;     GEMM_STORE(ra1, rb1, 1);
;     GEMM_LOAD(ra1, rb1, kt + 3);
;     __syncthreads();
;     GEMM_COMPUTE(1);
;     GEMM_STORE(ra0, rb0, 0);
;     GEMM_LOAD(ra0, rb0, (kt + 4 < nkm1 ? kt + 4 : nkm1));
;     __syncthreads();
;   }
.LBB0_244:
	s_add_i32 s0, s0, 2
	s_min_u32 s1, s0, 11
	s_lshl_b32 s94, s1, 7
	s_cmp_lt_u32 s0, 12
	s_waitcnt lgkmcnt(3)
	v_mfma_f32_16x16x32_bf16 v[118:121], v[170:173], v[188:191], v[118:121]
	v_mfma_f32_16x16x32_bf16 v[106:109], v[170:173], v[192:195], v[106:109]
	v_mfma_f32_16x16x32_bf16 v[98:101], v[170:173], v[196:199], v[98:101]
	v_mfma_f32_16x16x32_bf16 v[90:93], v[170:173], v[200:203], v[90:93]
	ds_read_b128 v[230:233], v160
	ds_read_b128 v[204:207], v161 offset:16384
	ds_read_b128 v[208:211], v161 offset:18432
	ds_read_b128 v[216:219], v161 offset:20480
	ds_read_b128 v[220:223], v161 offset:22528
	s_waitcnt lgkmcnt(7)
	v_mfma_f32_16x16x32_bf16 v[94:97], v[174:177], v[188:191], v[94:97]
	v_mfma_f32_16x16x32_bf16 v[114:117], v[174:177], v[192:195], v[114:117]
	v_mfma_f32_16x16x32_bf16 v[110:113], v[174:177], v[196:199], v[110:113]
	v_mfma_f32_16x16x32_bf16 v[102:105], v[174:177], v[200:203], v[102:105]
	s_waitcnt lgkmcnt(6)
	v_mfma_f32_16x16x32_bf16 v[122:125], v[178:181], v[188:191], v[122:125]
	v_mfma_f32_16x16x32_bf16 v[126:129], v[178:181], v[192:195], v[126:129]
	v_mfma_f32_16x16x32_bf16 v[86:89], v[178:181], v[196:199], v[86:89]
	v_mfma_f32_16x16x32_bf16 v[82:85], v[178:181], v[200:203], v[82:85]
	ds_read_b128 v[242:245], v160 offset:2048
	ds_read_b128 v[234:237], v160 offset:4096
	ds_read_b128 v[238:241], v160 offset:6144
	s_waitcnt lgkmcnt(8)
	v_mfma_f32_16x16x32_bf16 v[74:77], v[182:185], v[188:191], v[74:77]
	v_mfma_f32_16x16x32_bf16 v[70:73], v[182:185], v[192:195], v[70:73]
	v_mfma_f32_16x16x32_bf16 v[66:69], v[182:185], v[196:199], v[66:69]
	v_mfma_f32_16x16x32_bf16 v[78:81], v[182:185], v[200:203], v[78:81]
	s_waitcnt lgkmcnt(3)
	v_mfma_f32_16x16x32_bf16 v[118:121], v[230:233], v[204:207], v[118:121]
	s_waitcnt vmcnt(8)
	ds_write_b128 v163, v[2:5] offset:32768
	ds_write_b128 v163, v[26:29] offset:36864
	ds_write_b128 v163, v[22:25] offset:40960
	ds_write_b128 v163, v[18:21] offset:45056
	v_mfma_f32_16x16x32_bf16 v[106:109], v[230:233], v[208:211], v[106:109]
	ds_write_b128 v163, v[6:9] offset:49152
	ds_write_b128 v163, v[14:17] offset:53248
	ds_write_b128 v163, v[10:13] offset:57344
	v_lshl_add_u64 v[6:7], v[154:155], 0, v[0:1]
	v_mfma_f32_16x16x32_bf16 v[98:101], v[230:233], v[216:219], v[98:101]
	v_add_co_u32_e32 v12, vcc, s15, v6
	v_lshl_add_u64 v[10:11], v[152:153], 0, v[0:1]
	s_nop 0
	v_addc_co_u32_e32 v13, vcc, 0, v7, vcc
	v_add_co_u32_e32 v14, vcc, s16, v6
	v_mfma_f32_16x16x32_bf16 v[90:93], v[230:233], v[220:223], v[90:93]
	ds_write_b128 v163, v[30:33] offset:61440
	s_nop 0
	v_addc_co_u32_e32 v15, vcc, 0, v7, vcc
	v_add_co_u32_e32 v16, vcc, s17, v6
	v_addc_co_u32_e32 v17, vcc, 0, v7, vcc
	s_waitcnt lgkmcnt(10)
	v_mfma_f32_16x16x32_bf16 v[94:97], v[242:245], v[204:207], v[94:97]
	v_add_co_u32_e32 v30, vcc, s15, v10
	v_addc_co_u32_e32 v31, vcc, 0, v11, vcc
	v_add_co_u32_e32 v32, vcc, s16, v10
	v_addc_co_u32_e32 v33, vcc, 0, v11, vcc
	v_mfma_f32_16x16x32_bf16 v[114:117], v[242:245], v[208:211], v[114:117]
	global_load_dwordx4 v[2:5], v[6:7], off offset:384
	v_add_co_u32_e32 v166, vcc, s17, v10
	global_load_dwordx4 v[6:9], v[10:11], off offset:384
	s_nop 0
	v_addc_co_u32_e32 v167, vcc, 0, v11, vcc
	v_mfma_f32_16x16x32_bf16 v[110:113], v[242:245], v[216:219], v[110:113]
	global_load_dwordx4 v[26:29], v[12:13], off offset:384
	global_load_dwordx4 v[22:25], v[14:15], off offset:384
	global_load_dwordx4 v[18:21], v[16:17], off offset:384
	s_nop 0
	global_load_dwordx4 v[14:17], v[30:31], off offset:384
	v_mfma_f32_16x16x32_bf16 v[102:105], v[242:245], v[220:223], v[102:105]
	global_load_dwordx4 v[10:13], v[32:33], off offset:384
	s_nop 0
	global_load_dwordx4 v[30:33], v[166:167], off offset:384
	s_waitcnt lgkmcnt(0)
	s_barrier
	ds_read_b128 v[170:173], v162 offset:32768
	ds_read_b128 v[188:191], v164 offset:49152
	ds_read_b128 v[192:195], v164 offset:51200
	ds_read_b128 v[196:199], v164 offset:53248
	ds_read_b128 v[200:203], v164 offset:55296
	ds_read_b128 v[174:177], v162 offset:34816
	ds_read_b128 v[178:181], v162 offset:36864
	ds_read_b128 v[182:185], v162 offset:38912
	v_mfma_f32_16x16x32_bf16 v[122:125], v[234:237], v[204:207], v[122:125]
	v_mfma_f32_16x16x32_bf16 v[126:129], v[234:237], v[208:211], v[126:129]
	v_mfma_f32_16x16x32_bf16 v[86:89], v[234:237], v[216:219], v[86:89]
	v_mfma_f32_16x16x32_bf16 v[82:85], v[234:237], v[220:223], v[82:85]
	v_mfma_f32_16x16x32_bf16 v[74:77], v[238:241], v[204:207], v[74:77]
	v_mfma_f32_16x16x32_bf16 v[70:73], v[238:241], v[208:211], v[70:73]
	v_mfma_f32_16x16x32_bf16 v[66:69], v[238:241], v[216:219], v[66:69]
	v_mfma_f32_16x16x32_bf16 v[78:81], v[238:241], v[220:223], v[78:81]
	s_waitcnt lgkmcnt(3)
	v_mfma_f32_16x16x32_bf16 v[118:121], v[170:173], v[188:191], v[118:121]
	v_mfma_f32_16x16x32_bf16 v[106:109], v[170:173], v[192:195], v[106:109]
	v_mfma_f32_16x16x32_bf16 v[98:101], v[170:173], v[196:199], v[98:101]
	v_mfma_f32_16x16x32_bf16 v[90:93], v[170:173], v[200:203], v[90:93]
	ds_read_b128 v[230:233], v160 offset:32768
	ds_read_b128 v[204:207], v161 offset:49152
	ds_read_b128 v[208:211], v161 offset:51200
	ds_read_b128 v[216:219], v161 offset:53248
	ds_read_b128 v[220:223], v161 offset:55296
	s_waitcnt lgkmcnt(7)
	v_mfma_f32_16x16x32_bf16 v[94:97], v[174:177], v[188:191], v[94:97]
	v_mfma_f32_16x16x32_bf16 v[114:117], v[174:177], v[192:195], v[114:117]
	v_mfma_f32_16x16x32_bf16 v[110:113], v[174:177], v[196:199], v[110:113]
	v_mfma_f32_16x16x32_bf16 v[102:105], v[174:177], v[200:203], v[102:105]
	s_waitcnt lgkmcnt(6)
; template <int NT, bool BKN, bool MASK = false, bool ROWSS = false, class Epi> ...
;     ...
;   for (int kt = 0; kt < nk - 2; kt += 2) {
;     GEMM_COMPUTE(0);
;     GEMM_STORE(ra1, rb1, 1);
;     GEMM_LOAD(ra1, rb1, kt + 3);
;     __syncthreads();
;     GEMM_COMPUTE(1);
;     GEMM_STORE(ra0, rb0, 0);
;     GEMM_LOAD(ra0, rb0, (kt + 4 < nkm1 ? kt + 4 : nkm1));
;     __syncthreads();
;   }
;   GEMM_COMPUTE(0);
;   GEMM_STORE(ra1, rb1, 1);
;   __syncthreads();
;   GEMM_COMPUTE(1);
	v_mfma_f32_16x16x32_bf16 v[122:125], v[178:181], v[188:191], v[122:125]
	v_mfma_f32_16x16x32_bf16 v[126:129], v[178:181], v[192:195], v[126:129]
	v_mfma_f32_16x16x32_bf16 v[86:89], v[178:181], v[196:199], v[86:89]
	v_mfma_f32_16x16x32_bf16 v[82:85], v[178:181], v[200:203], v[82:85]
	ds_read_b128 v[242:245], v160 offset:34816
	ds_read_b128 v[234:237], v160 offset:36864
	ds_read_b128 v[238:241], v160 offset:38912
	s_waitcnt lgkmcnt(8)
	v_mfma_f32_16x16x32_bf16 v[74:77], v[182:185], v[188:191], v[74:77]
	v_mfma_f32_16x16x32_bf16 v[70:73], v[182:185], v[192:195], v[70:73]
	v_mfma_f32_16x16x32_bf16 v[66:69], v[182:185], v[196:199], v[66:69]
	v_mfma_f32_16x16x32_bf16 v[78:81], v[182:185], v[200:203], v[78:81]
	s_waitcnt lgkmcnt(3)
	v_mfma_f32_16x16x32_bf16 v[118:121], v[230:233], v[204:207], v[118:121]
	v_lshl_add_u64 v[152:153], v[152:153], 0, s[6:7]
	v_lshl_add_u64 v[154:155], v[154:155], 0, s[6:7]
	s_waitcnt vmcnt(8)
	ds_write_b128 v163, v[34:37]
	ds_write_b128 v163, v[38:41] offset:4096
	v_mfma_f32_16x16x32_bf16 v[106:109], v[230:233], v[208:211], v[106:109]
	ds_write_b128 v163, v[46:49] offset:8192
	ds_write_b128 v163, v[42:45] offset:12288
	ds_write_b128 v163, v[50:53] offset:16384
	ds_write_b128 v163, v[58:61] offset:20480
	v_mfma_f32_16x16x32_bf16 v[98:101], v[230:233], v[216:219], v[98:101]
	ds_write_b128 v163, v[54:57] offset:24576
	ds_write_b128 v163, v[62:65] offset:28672
	v_lshl_add_u64 v[34:35], v[136:137], 0, s[94:95]
	v_lshl_add_u64 v[38:39], v[138:139], 0, s[94:95]
	v_mfma_f32_16x16x32_bf16 v[90:93], v[230:233], v[220:223], v[90:93]
	v_lshl_add_u64 v[42:43], v[140:141], 0, s[94:95]
	v_lshl_add_u64 v[44:45], v[142:143], 0, s[94:95]
	v_lshl_add_u64 v[50:51], v[144:145], 0, s[94:95]
	v_lshl_add_u64 v[54:55], v[146:147], 0, s[94:95]
	s_waitcnt lgkmcnt(10)
	v_mfma_f32_16x16x32_bf16 v[94:97], v[242:245], v[204:207], v[94:97]
	v_lshl_add_u64 v[56:57], v[148:149], 0, s[94:95]
	v_lshl_add_u64 v[62:63], v[150:151], 0, s[94:95]
	v_mfma_f32_16x16x32_bf16 v[114:117], v[242:245], v[208:211], v[114:117]
	s_nop 0
	v_mfma_f32_16x16x32_bf16 v[110:113], v[242:245], v[216:219], v[110:113]
	s_nop 0
	v_mfma_f32_16x16x32_bf16 v[102:105], v[242:245], v[220:223], v[102:105]
	s_cbranch_scc0 .Lgd_lbb0_244
	global_load_dwordx4 v[34:37], v[34:35], off offset:512
	s_nop 0
	global_load_dwordx4 v[38:41], v[38:39], off offset:512
	s_nop 0
	global_load_dwordx4 v[46:49], v[42:43], off offset:512
	s_nop 0
	global_load_dwordx4 v[42:45], v[44:45], off offset:512
	s_nop 0
	global_load_dwordx4 v[50:53], v[50:51], off offset:512
	s_nop 0
	global_load_dwordx4 v[58:61], v[54:55], off offset:512
	s_nop 0
	global_load_dwordx4 v[54:57], v[56:57], off offset:512
	s_nop 0
	global_load_dwordx4 v[62:65], v[62:63], off offset:512
	s_nop 0
.Lgd_lbb0_244:
	s_waitcnt lgkmcnt(0)
	s_barrier
	ds_read_b128 v[170:173], v162
	ds_read_b128 v[188:191], v164 offset:16384
	ds_read_b128 v[192:195], v164 offset:18432
	ds_read_b128 v[196:199], v164 offset:20480
	ds_read_b128 v[200:203], v164 offset:22528
	ds_read_b128 v[174:177], v162 offset:2048
	ds_read_b128 v[178:181], v162 offset:4096
	ds_read_b128 v[182:185], v162 offset:6144
	v_mfma_f32_16x16x32_bf16 v[122:125], v[234:237], v[204:207], v[122:125]
	v_mfma_f32_16x16x32_bf16 v[126:129], v[234:237], v[208:211], v[126:129]
	v_mfma_f32_16x16x32_bf16 v[86:89], v[234:237], v[216:219], v[86:89]
	v_mfma_f32_16x16x32_bf16 v[82:85], v[234:237], v[220:223], v[82:85]
	v_mfma_f32_16x16x32_bf16 v[74:77], v[238:241], v[204:207], v[74:77]
	v_mfma_f32_16x16x32_bf16 v[70:73], v[238:241], v[208:211], v[70:73]
	v_mfma_f32_16x16x32_bf16 v[66:69], v[238:241], v[216:219], v[66:69]
	v_mfma_f32_16x16x32_bf16 v[78:81], v[238:241], v[220:223], v[78:81]
	s_cbranch_scc1 .LBB0_244
	s_waitcnt vmcnt(0)
	ds_read_b128 v[34:37], v162
	ds_read_b128 v[38:41], v164 offset:16384
	ds_read_b128 v[46:49], v164 offset:18432
	ds_read_b128 v[54:57], v164 offset:20480
	ds_read_b128 v[62:65], v164 offset:22528
	s_cmp_lt_i32 s40, 4
	s_waitcnt lgkmcnt(3)
	v_mfma_f32_16x16x32_bf16 v[42:45], v[34:37], v[38:41], v[118:121]
	s_cselect_b64 s[0:1], -1, 0
	s_cmp_gt_i32 s40, 3
	s_cselect_b64 s[46:47], -1, 0
	s_waitcnt lgkmcnt(2)
	v_mfma_f32_16x16x32_bf16 v[50:53], v[34:37], v[46:49], v[106:109]
	s_and_b64 vcc, exec, s[46:47]
	s_waitcnt lgkmcnt(1)
	v_mfma_f32_16x16x32_bf16 v[58:61], v[34:37], v[54:57], v[98:101]
	s_waitcnt lgkmcnt(0)
	v_mfma_f32_16x16x32_bf16 v[34:37], v[34:37], v[62:65], v[90:93]
	s_nop 2
	ds_read_b128 v[90:93], v162 offset:2048
	s_waitcnt lgkmcnt(0)
	v_mfma_f32_16x16x32_bf16 v[94:97], v[90:93], v[38:41], v[94:97]
	v_mfma_f32_16x16x32_bf16 v[98:101], v[90:93], v[46:49], v[114:117]
	v_mfma_f32_16x16x32_bf16 v[106:109], v[90:93], v[54:57], v[110:113]
	v_mfma_f32_16x16x32_bf16 v[90:93], v[90:93], v[62:65], v[102:105]
	s_nop 2
	ds_read_b128 v[102:105], v162 offset:4096
	s_waitcnt lgkmcnt(0)
	v_mfma_f32_16x16x32_bf16 v[110:113], v[102:105], v[38:41], v[122:125]
	v_mfma_f32_16x16x32_bf16 v[114:117], v[102:105], v[46:49], v[126:129]
	v_mfma_f32_16x16x32_bf16 v[86:89], v[102:105], v[54:57], v[86:89]
	v_mfma_f32_16x16x32_bf16 v[82:85], v[102:105], v[62:65], v[82:85]
	ds_read_b128 v[102:105], v162 offset:6144
	s_waitcnt lgkmcnt(0)
	v_mfma_f32_16x16x32_bf16 v[54:57], v[102:105], v[54:57], v[66:69]
	s_nop 2
	ds_read_b128 v[66:69], v160
	v_mfma_f32_16x16x32_bf16 v[38:41], v[102:105], v[38:41], v[74:77]
	v_mfma_f32_16x16x32_bf16 v[46:49], v[102:105], v[46:49], v[70:73]
	s_nop 1
	ds_read_b128 v[74:77], v161 offset:18432
	v_mfma_f32_16x16x32_bf16 v[62:65], v[102:105], v[62:65], v[78:81]
	ds_read_b128 v[70:73], v161 offset:16384
	ds_read_b128 v[102:105], v161 offset:22528
	s_nop 0
	ds_read_b128 v[78:81], v161 offset:20480
	s_waitcnt lgkmcnt(2)
; __device__ __forceinline__ float gelu_tanh(float x) {
;   float y = 0.7978845608028654f * (x + 0.044715f * x * x * x);
;   return x / (1.f + __expf(-2.f * y));
; }
; template <int NT, bool BKN, bool MASK = false, bool ROWSS = false, class Epi> ...
;     ...
;   GEMM_COMPUTE(0);
;   GEMM_STORE(ra1, rb1, 1);
;   __syncthreads();
;   GEMM_COMPUTE(1);
	v_mfma_f32_16x16x32_bf16 v[42:45], v[66:69], v[70:73], v[42:45]
	v_mfma_f32_16x16x32_bf16 v[50:53], v[66:69], v[74:77], v[50:53]
	s_waitcnt lgkmcnt(0)
	v_mfma_f32_16x16x32_bf16 v[58:61], v[66:69], v[78:81], v[58:61]
	v_mfma_f32_16x16x32_bf16 v[34:37], v[66:69], v[102:105], v[34:37]
	ds_read_b128 v[66:69], v160 offset:2048
	s_waitcnt lgkmcnt(0)
	v_mfma_f32_16x16x32_bf16 v[94:97], v[66:69], v[70:73], v[94:97]
	v_mfma_f32_16x16x32_bf16 v[98:101], v[66:69], v[74:77], v[98:101]
	v_mfma_f32_16x16x32_bf16 v[106:109], v[66:69], v[78:81], v[106:109]
	v_mfma_f32_16x16x32_bf16 v[66:69], v[66:69], v[102:105], v[90:93]
	s_nop 2
	ds_read_b128 v[90:93], v160 offset:4096
	s_waitcnt lgkmcnt(0)
	v_mfma_f32_16x16x32_bf16 v[110:113], v[90:93], v[70:73], v[110:113]
	v_mfma_f32_16x16x32_bf16 v[114:117], v[90:93], v[74:77], v[114:117]
	v_mfma_f32_16x16x32_bf16 v[86:89], v[90:93], v[78:81], v[86:89]
	v_mfma_f32_16x16x32_bf16 v[82:85], v[90:93], v[102:105], v[82:85]
	ds_read_b128 v[90:93], v160 offset:6144
	ds_write_b128 v163, v[2:5] offset:32768
	ds_write_b128 v163, v[26:29] offset:36864
	ds_write_b128 v163, v[22:25] offset:40960
	ds_write_b128 v163, v[18:21] offset:45056
	ds_write_b128 v163, v[6:9] offset:49152
	ds_write_b128 v163, v[14:17] offset:53248
	ds_write_b128 v163, v[10:13] offset:57344
	ds_write_b128 v163, v[30:33] offset:61440
	s_waitcnt lgkmcnt(0)
	s_barrier
	ds_read_b128 v[2:5], v162 offset:32768
	ds_read_b128 v[10:13], v164 offset:49152
	s_waitcnt lgkmcnt(0)
	v_mfma_f32_16x16x32_bf16 v[14:17], v[2:5], v[10:13], v[42:45]
	ds_read_b128 v[18:21], v164 offset:51200
	ds_read_b128 v[26:29], v164 offset:53248
	s_nop 0
	ds_read_b128 v[42:45], v164 offset:55296
	s_waitcnt lgkmcnt(2)
	v_mfma_f32_16x16x32_bf16 v[22:25], v[2:5], v[18:21], v[50:53]
	s_nop 2
	ds_read_b128 v[50:53], v162 offset:36864
	s_waitcnt lgkmcnt(2)
	v_mfma_f32_16x16x32_bf16 v[30:33], v[2:5], v[26:29], v[58:61]
	s_waitcnt lgkmcnt(1)
	v_mfma_f32_16x16x32_bf16 v[2:5], v[2:5], v[42:45], v[34:37]
	s_nop 2
	ds_read_b128 v[34:37], v162 offset:34816
	v_mfma_f32_16x16x32_bf16 v[38:41], v[90:93], v[70:73], v[38:41]
	v_mfma_f32_16x16x32_bf16 v[46:49], v[90:93], v[74:77], v[46:49]
	v_mfma_f32_16x16x32_bf16 v[54:57], v[90:93], v[78:81], v[54:57]
	v_mfma_f32_16x16x32_bf16 v[6:9], v[90:93], v[102:105], v[62:65]
	s_waitcnt lgkmcnt(0)
	v_mfma_f32_16x16x32_bf16 v[70:73], v[34:37], v[10:13], v[94:97]
	v_mfma_f32_16x16x32_bf16 v[74:77], v[34:37], v[18:21], v[98:101]
	v_mfma_f32_16x16x32_bf16 v[78:81], v[34:37], v[26:29], v[106:109]
	v_mfma_f32_16x16x32_bf16 v[34:37], v[34:37], v[42:45], v[66:69]
	s_nop 1
	ds_read_b128 v[106:109], v161 offset:51200
	v_mfma_f32_16x16x32_bf16 v[66:69], v[50:53], v[10:13], v[110:113]
	v_mfma_f32_16x16x32_bf16 v[90:93], v[50:53], v[18:21], v[114:117]
	s_nop 1
	ds_read_b128 v[110:113], v161 offset:53248
	ds_read_b128 v[114:117], v161 offset:55296
	v_mfma_f32_16x16x32_bf16 v[86:89], v[50:53], v[26:29], v[86:89]
	v_mfma_f32_16x16x32_bf16 v[82:85], v[50:53], v[42:45], v[82:85]
	ds_read_b128 v[50:53], v162 offset:38912
	s_waitcnt lgkmcnt(0)
	v_mfma_f32_16x16x32_bf16 v[94:97], v[50:53], v[18:21], v[46:49]
	ds_read_b128 v[18:21], v160 offset:32768
	v_mfma_f32_16x16x32_bf16 v[10:13], v[50:53], v[10:13], v[38:41]
	v_mfma_f32_16x16x32_bf16 v[98:101], v[50:53], v[26:29], v[54:57]
	v_mfma_f32_16x16x32_bf16 v[102:105], v[50:53], v[42:45], v[6:9]
	s_nop 2
	ds_read_b128 v[6:9], v161 offset:49152
	s_waitcnt lgkmcnt(1)
	v_mfma_f32_16x16x32_bf16 v[50:53], v[18:21], v[114:117], v[2:5]
	s_nop 2
	ds_read_b128 v[2:5], v160 offset:34816
	s_waitcnt lgkmcnt(0)
	v_mfma_f32_16x16x32_bf16 v[46:49], v[2:5], v[6:9], v[70:73]
	v_mfma_f32_16x16x32_bf16 v[42:45], v[2:5], v[106:109], v[74:77]
	v_mfma_f32_16x16x32_bf16 v[38:41], v[2:5], v[110:113], v[78:81]
	v_mfma_f32_16x16x32_bf16 v[34:37], v[2:5], v[114:117], v[34:37]
	ds_read_b128 v[2:5], v160 offset:36864
	v_mfma_f32_16x16x32_bf16 v[62:65], v[18:21], v[6:9], v[14:17]
	v_mfma_f32_16x16x32_bf16 v[58:61], v[18:21], v[106:109], v[22:25]
	v_mfma_f32_16x16x32_bf16 v[54:57], v[18:21], v[110:113], v[30:33]
	s_waitcnt lgkmcnt(0)
	v_mfma_f32_16x16x32_bf16 v[30:33], v[2:5], v[6:9], v[66:69]
	v_mfma_f32_16x16x32_bf16 v[26:29], v[2:5], v[106:109], v[90:93]
	s_nop 1
	v_mov_b32_e32 v66, v187
	v_mfma_f32_16x16x32_bf16 v[22:25], v[2:5], v[110:113], v[86:89]
	v_mfma_f32_16x16x32_bf16 v[18:21], v[2:5], v[114:117], v[82:85]
	ds_read_b128 v[2:5], v160 offset:38912
	s_waitcnt lgkmcnt(0)
	v_mfma_f32_16x16x32_bf16 v[14:17], v[2:5], v[6:9], v[10:13]
	s_barrier
	v_mfma_f32_16x16x32_bf16 v[10:13], v[2:5], v[106:109], v[94:97]
	v_mfma_f32_16x16x32_bf16 v[6:9], v[2:5], v[110:113], v[98:101]
	v_mfma_f32_16x16x32_bf16 v[2:5], v[2:5], v[114:117], v[102:105]
	s_cbranch_vccnz .LBB0_247
	v_mul_f32_e32 v0, 0x3d372713, v62
	v_mul_f32_e32 v0, v62, v0
	v_fma_f32 v0, v62, v0, v62
	v_mul_f32_e32 v0, 0x3f4c422a, v0
	v_mul_f32_e32 v0, -2.0, v0
	v_mul_f32_e32 v0, 0x3fb8aa3b, v0
	v_exp_f32_e32 v0, v0
	s_nop 0
	v_add_f32_e32 v0, 1.0, v0
	v_div_scale_f32 v67, s[18:19], v0, v0, v62
	v_rcp_f32_e32 v68, v67
	v_div_scale_f32 v69, vcc, v62, v0, v62
	v_fma_f32 v70, -v67, v68, 1.0
	v_fmac_f32_e32 v68, v70, v68
	v_mul_f32_e32 v70, v69, v68
	v_fma_f32 v71, -v67, v70, v69
	v_fmac_f32_e32 v70, v71, v68
	v_fma_f32 v67, -v67, v70, v69
	v_div_fmas_f32 v67, v67, v68, v70
	v_div_fixup_f32 v62, v67, v0, v62

; template <int NT, bool BKN, bool MASK = false, bool ROWSS = false, class Epi> ...
;     ...
;   float ss_[4] = {0.f, 0.f, 0.f, 0.f};
;   int stk_ = 0;
;   f32x4 acc[4][NT];
; #pragma unroll
;   for (int i = 0; i < 4; ++i)
; #pragma unroll
;     for (int j = 0; j < NT; ++j) acc[i][j] = (f32x4){0.f, 0.f, 0.f, 0.f};
;   const int nk = K >> 6;
;   const int nkm1 = nk - 1;
;   __syncthreads();
;   GEMM_LOAD(ra0, rb0, 0);
;   GEMM_LOAD(ra1, rb1, 1);
;   GEMM_STORE(ra0, rb0, 0);
;   GEMM_LOAD(ra0, rb0, (2 < nkm1 ? 2 : nkm1));
;   __syncthreads();
;   for (int kt = 0; kt < nk - 2; kt += 2) {
;     GEMM_COMPUTE(0);
;     GEMM_STORE(ra1, rb1, 1);
;     GEMM_LOAD(ra1, rb1, kt + 3);
;     __syncthreads();
;     GEMM_COMPUTE(1);
;     GEMM_STORE(ra0, rb0, 0);
;     GEMM_LOAD(ra0, rb0, (kt + 4 < nkm1 ? kt + 4 : nkm1));
;     __syncthreads();
;   }
.LBB0_846:
	s_add_i32 s8, s8, 2
	s_min_u32 s9, s8, 11
	s_lshl_b32 s94, s9, 7
	s_cmp_lt_u32 s8, 12
	s_waitcnt lgkmcnt(3)
	v_mfma_f32_16x16x32_bf16 v[122:125], v[168:171], v[188:191], v[122:125]
	v_mfma_f32_16x16x32_bf16 v[110:113], v[168:171], v[192:195], v[110:113]
	v_mfma_f32_16x16x32_bf16 v[102:105], v[168:171], v[196:199], v[102:105]
	v_mfma_f32_16x16x32_bf16 v[94:97], v[168:171], v[200:203], v[94:97]
	ds_read_b128 v[236:239], v163
	ds_read_b128 v[204:207], v164 offset:16384
	ds_read_b128 v[208:211], v164 offset:18432
	ds_read_b128 v[216:219], v164 offset:20480
	ds_read_b128 v[220:223], v164 offset:22528
	s_waitcnt lgkmcnt(7)
	v_mfma_f32_16x16x32_bf16 v[98:101], v[172:175], v[188:191], v[98:101]
	v_mfma_f32_16x16x32_bf16 v[118:121], v[172:175], v[192:195], v[118:121]
	v_mfma_f32_16x16x32_bf16 v[114:117], v[172:175], v[196:199], v[114:117]
	v_mfma_f32_16x16x32_bf16 v[106:109], v[172:175], v[200:203], v[106:109]
	s_waitcnt lgkmcnt(6)
	v_mfma_f32_16x16x32_bf16 v[126:129], v[176:179], v[188:191], v[126:129]
	v_mfma_f32_16x16x32_bf16 v[82:85], v[176:179], v[192:195], v[82:85]
	v_mfma_f32_16x16x32_bf16 v[90:93], v[176:179], v[196:199], v[90:93]
	v_mfma_f32_16x16x32_bf16 v[86:89], v[176:179], v[200:203], v[86:89]
	ds_read_b128 v[172:175], v163 offset:2048
	ds_read_b128 v[240:243], v163 offset:4096
	ds_read_b128 v[244:247], v163 offset:6144
	s_waitcnt lgkmcnt(8)
	v_mfma_f32_16x16x32_bf16 v[74:77], v[180:183], v[188:191], v[74:77]
	v_mfma_f32_16x16x32_bf16 v[70:73], v[180:183], v[192:195], v[70:73]
	v_mfma_f32_16x16x32_bf16 v[66:69], v[180:183], v[196:199], v[66:69]
	v_mfma_f32_16x16x32_bf16 v[78:81], v[180:183], v[200:203], v[78:81]
	s_waitcnt lgkmcnt(3)
	v_mfma_f32_16x16x32_bf16 v[122:125], v[236:239], v[204:207], v[122:125]
	s_waitcnt vmcnt(8)
	ds_write_b128 v167, v[6:9] offset:32768
	ds_write_b128 v167, v[26:29] offset:36864
	ds_write_b128 v167, v[22:25] offset:40960
	ds_write_b128 v167, v[30:33] offset:45056
	v_mfma_f32_16x16x32_bf16 v[110:113], v[236:239], v[208:211], v[110:113]
	ds_write_b128 v167, v[2:5] offset:49152
	ds_write_b128 v167, v[14:17] offset:53248
	ds_write_b128 v167, v[10:13] offset:57344
	v_lshl_add_u64 v[2:3], v[156:157], 0, v[0:1]
	v_mfma_f32_16x16x32_bf16 v[102:105], v[236:239], v[216:219], v[102:105]
	v_add_co_u32_e32 v12, vcc, s15, v2
	v_lshl_add_u64 v[10:11], v[154:155], 0, v[0:1]
	s_nop 0
	v_addc_co_u32_e32 v13, vcc, 0, v3, vcc
	v_add_co_u32_e32 v14, vcc, s16, v2
	v_mfma_f32_16x16x32_bf16 v[94:97], v[236:239], v[220:223], v[94:97]
	ds_write_b128 v167, v[18:21] offset:61440
	s_nop 0
	v_addc_co_u32_e32 v15, vcc, 0, v3, vcc
	v_add_co_u32_e32 v16, vcc, s17, v2
	v_addc_co_u32_e32 v17, vcc, 0, v3, vcc
	s_waitcnt lgkmcnt(10)
	v_mfma_f32_16x16x32_bf16 v[98:101], v[172:175], v[204:207], v[98:101]
	v_add_co_u32_e32 v18, vcc, s15, v10
	v_addc_co_u32_e32 v19, vcc, 0, v11, vcc
	v_add_co_u32_e32 v20, vcc, s16, v10
	v_addc_co_u32_e32 v21, vcc, 0, v11, vcc
	v_mfma_f32_16x16x32_bf16 v[118:121], v[172:175], v[208:211], v[118:121]
	global_load_dwordx4 v[6:9], v[2:3], off offset:384
	v_add_co_u32_e32 v184, vcc, s17, v10
	global_load_dwordx4 v[2:5], v[10:11], off offset:384
	s_nop 0
	v_addc_co_u32_e32 v185, vcc, 0, v11, vcc
	v_mfma_f32_16x16x32_bf16 v[114:117], v[172:175], v[216:219], v[114:117]
	global_load_dwordx4 v[26:29], v[12:13], off offset:384
	global_load_dwordx4 v[22:25], v[14:15], off offset:384
	global_load_dwordx4 v[30:33], v[16:17], off offset:384
	s_nop 0
	global_load_dwordx4 v[14:17], v[18:19], off offset:384
	v_mfma_f32_16x16x32_bf16 v[106:109], v[172:175], v[220:223], v[106:109]
	global_load_dwordx4 v[10:13], v[20:21], off offset:384
	s_nop 0
	global_load_dwordx4 v[18:21], v[184:185], off offset:384
	s_waitcnt lgkmcnt(0)
	s_barrier
	ds_read_b128 v[168:171], v165 offset:32768
	ds_read_b128 v[188:191], v166 offset:49152
	ds_read_b128 v[192:195], v166 offset:51200
	ds_read_b128 v[196:199], v166 offset:53248
	ds_read_b128 v[200:203], v166 offset:55296
	ds_read_b128 v[172:175], v165 offset:34816
	ds_read_b128 v[176:179], v165 offset:36864
	ds_read_b128 v[180:183], v165 offset:38912
	v_mfma_f32_16x16x32_bf16 v[126:129], v[240:243], v[204:207], v[126:129]
	v_mfma_f32_16x16x32_bf16 v[82:85], v[240:243], v[208:211], v[82:85]
	v_mfma_f32_16x16x32_bf16 v[90:93], v[240:243], v[216:219], v[90:93]
	v_mfma_f32_16x16x32_bf16 v[86:89], v[240:243], v[220:223], v[86:89]
	v_mfma_f32_16x16x32_bf16 v[74:77], v[244:247], v[204:207], v[74:77]
	v_mfma_f32_16x16x32_bf16 v[70:73], v[244:247], v[208:211], v[70:73]
	v_mfma_f32_16x16x32_bf16 v[66:69], v[244:247], v[216:219], v[66:69]
	v_mfma_f32_16x16x32_bf16 v[78:81], v[244:247], v[220:223], v[78:81]
	s_waitcnt lgkmcnt(3)
	v_mfma_f32_16x16x32_bf16 v[122:125], v[168:171], v[188:191], v[122:125]
	v_mfma_f32_16x16x32_bf16 v[110:113], v[168:171], v[192:195], v[110:113]
	v_mfma_f32_16x16x32_bf16 v[102:105], v[168:171], v[196:199], v[102:105]
	v_mfma_f32_16x16x32_bf16 v[94:97], v[168:171], v[200:203], v[94:97]
	ds_read_b128 v[236:239], v163 offset:32768
	ds_read_b128 v[204:207], v164 offset:49152
	ds_read_b128 v[208:211], v164 offset:51200
	ds_read_b128 v[216:219], v164 offset:53248
	ds_read_b128 v[220:223], v164 offset:55296
	s_waitcnt lgkmcnt(7)
	v_mfma_f32_16x16x32_bf16 v[98:101], v[172:175], v[188:191], v[98:101]
	v_mfma_f32_16x16x32_bf16 v[118:121], v[172:175], v[192:195], v[118:121]
	v_mfma_f32_16x16x32_bf16 v[114:117], v[172:175], v[196:199], v[114:117]
	v_mfma_f32_16x16x32_bf16 v[106:109], v[172:175], v[200:203], v[106:109]
	s_waitcnt lgkmcnt(6)
; template <int NT, bool BKN, bool MASK = false, bool ROWSS = false, class Epi> ...
;     ...
;   for (int kt = 0; kt < nk - 2; kt += 2) {
;     GEMM_COMPUTE(0);
;     GEMM_STORE(ra1, rb1, 1);
;     GEMM_LOAD(ra1, rb1, kt + 3);
;     __syncthreads();
;     GEMM_COMPUTE(1);
;     GEMM_STORE(ra0, rb0, 0);
;     GEMM_LOAD(ra0, rb0, (kt + 4 < nkm1 ? kt + 4 : nkm1));
;     __syncthreads();
;   }
;   GEMM_COMPUTE(0);
;   GEMM_STORE(ra1, rb1, 1);
;   __syncthreads();
;   GEMM_COMPUTE(1);
	v_mfma_f32_16x16x32_bf16 v[126:129], v[176:179], v[188:191], v[126:129]
	v_mfma_f32_16x16x32_bf16 v[82:85], v[176:179], v[192:195], v[82:85]
	v_mfma_f32_16x16x32_bf16 v[90:93], v[176:179], v[196:199], v[90:93]
	v_mfma_f32_16x16x32_bf16 v[86:89], v[176:179], v[200:203], v[86:89]
	ds_read_b128 v[172:175], v163 offset:34816
	ds_read_b128 v[240:243], v163 offset:36864
	ds_read_b128 v[244:247], v163 offset:38912
	s_waitcnt lgkmcnt(8)
	v_mfma_f32_16x16x32_bf16 v[74:77], v[180:183], v[188:191], v[74:77]
	v_mfma_f32_16x16x32_bf16 v[70:73], v[180:183], v[192:195], v[70:73]
	v_mfma_f32_16x16x32_bf16 v[66:69], v[180:183], v[196:199], v[66:69]
	v_mfma_f32_16x16x32_bf16 v[78:81], v[180:183], v[200:203], v[78:81]
	s_waitcnt lgkmcnt(3)
	v_mfma_f32_16x16x32_bf16 v[122:125], v[236:239], v[204:207], v[122:125]
	v_lshl_add_u64 v[154:155], v[154:155], 0, s[6:7]
	v_lshl_add_u64 v[156:157], v[156:157], 0, s[6:7]
	s_waitcnt vmcnt(8)
	ds_write_b128 v167, v[50:53]
	ds_write_b128 v167, v[54:57] offset:4096
	v_mfma_f32_16x16x32_bf16 v[110:113], v[236:239], v[208:211], v[110:113]
	ds_write_b128 v167, v[58:61] offset:8192
	ds_write_b128 v167, v[62:65] offset:12288
	ds_write_b128 v167, v[34:37] offset:16384
	ds_write_b128 v167, v[38:41] offset:20480
	v_mfma_f32_16x16x32_bf16 v[102:105], v[236:239], v[216:219], v[102:105]
	ds_write_b128 v167, v[42:45] offset:24576
	ds_write_b128 v167, v[46:49] offset:28672
	v_lshl_add_u64 v[34:35], v[146:147], 0, s[94:95]
	v_lshl_add_u64 v[36:37], v[148:149], 0, s[94:95]
	v_mfma_f32_16x16x32_bf16 v[94:97], v[236:239], v[220:223], v[94:97]
	v_lshl_add_u64 v[38:39], v[150:151], 0, s[94:95]
	v_lshl_add_u64 v[40:41], v[152:153], 0, s[94:95]
	v_lshl_add_u64 v[42:43], v[138:139], 0, s[94:95]
	v_lshl_add_u64 v[44:45], v[140:141], 0, s[94:95]
	s_waitcnt lgkmcnt(10)
	v_mfma_f32_16x16x32_bf16 v[98:101], v[172:175], v[204:207], v[98:101]
	v_lshl_add_u64 v[46:47], v[142:143], 0, s[94:95]
	v_lshl_add_u64 v[48:49], v[144:145], 0, s[94:95]
	v_mfma_f32_16x16x32_bf16 v[118:121], v[172:175], v[208:211], v[118:121]
	v_mfma_f32_16x16x32_bf16 v[114:117], v[172:175], v[216:219], v[114:117]
	s_nop 0
	v_mfma_f32_16x16x32_bf16 v[106:109], v[172:175], v[220:223], v[106:109]
	s_cbranch_scc0 .Lgd_lbb0_846
	global_load_dwordx4 v[50:53], v[34:35], off offset:512
	s_nop 0
	global_load_dwordx4 v[54:57], v[36:37], off offset:512
	s_nop 0
	global_load_dwordx4 v[58:61], v[38:39], off offset:512
	s_nop 0
	global_load_dwordx4 v[62:65], v[40:41], off offset:512
	s_nop 0
	global_load_dwordx4 v[34:37], v[42:43], off offset:512
	s_nop 0
	global_load_dwordx4 v[38:41], v[44:45], off offset:512
	s_nop 0
	global_load_dwordx4 v[42:45], v[46:47], off offset:512
	s_nop 0
	global_load_dwordx4 v[46:49], v[48:49], off offset:512
	s_nop 0
.Lgd_lbb0_846:
	s_waitcnt lgkmcnt(0)
	s_barrier
	ds_read_b128 v[168:171], v165
	ds_read_b128 v[188:191], v166 offset:16384
	ds_read_b128 v[192:195], v166 offset:18432
	ds_read_b128 v[196:199], v166 offset:20480
	ds_read_b128 v[200:203], v166 offset:22528
	ds_read_b128 v[172:175], v165 offset:2048
	ds_read_b128 v[176:179], v165 offset:4096
	ds_read_b128 v[180:183], v165 offset:6144
	v_mfma_f32_16x16x32_bf16 v[126:129], v[240:243], v[204:207], v[126:129]
	v_mfma_f32_16x16x32_bf16 v[82:85], v[240:243], v[208:211], v[82:85]
	v_mfma_f32_16x16x32_bf16 v[90:93], v[240:243], v[216:219], v[90:93]
	v_mfma_f32_16x16x32_bf16 v[86:89], v[240:243], v[220:223], v[86:89]
	v_mfma_f32_16x16x32_bf16 v[74:77], v[244:247], v[204:207], v[74:77]
	v_mfma_f32_16x16x32_bf16 v[70:73], v[244:247], v[208:211], v[70:73]
	v_mfma_f32_16x16x32_bf16 v[66:69], v[244:247], v[216:219], v[66:69]
	v_mfma_f32_16x16x32_bf16 v[78:81], v[244:247], v[220:223], v[78:81]
	s_cbranch_scc1 .LBB0_846
	s_waitcnt vmcnt(0)
	ds_read_b128 v[34:37], v165
	ds_read_b128 v[38:41], v166 offset:16384
	ds_read_b128 v[46:49], v166 offset:18432
	ds_read_b128 v[54:57], v166 offset:20480
	ds_read_b128 v[62:65], v166 offset:22528
	s_ashr_i32 s8, s19, 9
	s_waitcnt lgkmcnt(3)
	v_mfma_f32_16x16x32_bf16 v[42:45], v[34:37], v[38:41], v[122:125]
	s_mul_i32 s9, s36, 3
	s_add_i32 s8, s8, s9
	v_mov_b32_e32 v0, 0x6000
	s_waitcnt lgkmcnt(2)
	v_mfma_f32_16x16x32_bf16 v[50:53], v[34:37], v[46:49], v[110:113]
	s_lshl_b32 s94, s52, 9
	s_waitcnt lgkmcnt(1)
	v_mfma_f32_16x16x32_bf16 v[58:61], v[34:37], v[54:57], v[102:105]
	s_waitcnt lgkmcnt(0)
	v_mfma_f32_16x16x32_bf16 v[34:37], v[34:37], v[62:65], v[94:97]
	s_nop 2
	ds_read_b128 v[94:97], v165 offset:2048
	s_waitcnt lgkmcnt(0)
	v_mfma_f32_16x16x32_bf16 v[98:101], v[94:97], v[38:41], v[98:101]
	v_mfma_f32_16x16x32_bf16 v[102:105], v[94:97], v[46:49], v[118:121]
	v_mfma_f32_16x16x32_bf16 v[110:113], v[94:97], v[54:57], v[114:117]
	v_mfma_f32_16x16x32_bf16 v[94:97], v[94:97], v[62:65], v[106:109]
	s_nop 2
	ds_read_b128 v[106:109], v165 offset:4096
	s_waitcnt lgkmcnt(0)
	v_mfma_f32_16x16x32_bf16 v[114:117], v[106:109], v[38:41], v[126:129]
	v_mfma_f32_16x16x32_bf16 v[82:85], v[106:109], v[46:49], v[82:85]
	v_mfma_f32_16x16x32_bf16 v[90:93], v[106:109], v[54:57], v[90:93]
	v_mfma_f32_16x16x32_bf16 v[86:89], v[106:109], v[62:65], v[86:89]
	ds_read_b128 v[106:109], v165 offset:6144
	s_waitcnt lgkmcnt(0)
	v_mfma_f32_16x16x32_bf16 v[54:57], v[106:109], v[54:57], v[66:69]
	s_nop 2
	ds_read_b128 v[66:69], v163
	v_mfma_f32_16x16x32_bf16 v[38:41], v[106:109], v[38:41], v[74:77]
	v_mfma_f32_16x16x32_bf16 v[46:49], v[106:109], v[46:49], v[70:73]
	s_nop 1
	ds_read_b128 v[74:77], v164 offset:18432
	v_mfma_f32_16x16x32_bf16 v[62:65], v[106:109], v[62:65], v[78:81]
	ds_read_b128 v[70:73], v164 offset:16384
	ds_read_b128 v[106:109], v164 offset:22528
	s_nop 0
	ds_read_b128 v[78:81], v164 offset:20480
	s_waitcnt lgkmcnt(2)
	v_mfma_f32_16x16x32_bf16 v[42:45], v[66:69], v[70:73], v[42:45]
	v_mfma_f32_16x16x32_bf16 v[50:53], v[66:69], v[74:77], v[50:53]
	s_waitcnt lgkmcnt(0)
	v_mfma_f32_16x16x32_bf16 v[58:61], v[66:69], v[78:81], v[58:61]
	v_mfma_f32_16x16x32_bf16 v[34:37], v[66:69], v[106:109], v[34:37]
	ds_read_b128 v[66:69], v163 offset:2048
	s_waitcnt lgkmcnt(0)
	v_mfma_f32_16x16x32_bf16 v[98:101], v[66:69], v[70:73], v[98:101]
	v_mfma_f32_16x16x32_bf16 v[102:105], v[66:69], v[74:77], v[102:105]
	v_mfma_f32_16x16x32_bf16 v[110:113], v[66:69], v[78:81], v[110:113]
	v_mfma_f32_16x16x32_bf16 v[66:69], v[66:69], v[106:109], v[94:97]
	s_nop 2
	ds_read_b128 v[94:97], v163 offset:4096
	s_waitcnt lgkmcnt(0)
	v_mfma_f32_16x16x32_bf16 v[114:117], v[94:97], v[70:73], v[114:117]
	v_mfma_f32_16x16x32_bf16 v[82:85], v[94:97], v[74:77], v[82:85]
	v_mfma_f32_16x16x32_bf16 v[90:93], v[94:97], v[78:81], v[90:93]
	v_mfma_f32_16x16x32_bf16 v[86:89], v[94:97], v[106:109], v[86:89]
	ds_read_b128 v[94:97], v163 offset:6144
	ds_write_b128 v167, v[6:9] offset:32768
	ds_write_b128 v167, v[26:29] offset:36864
	ds_write_b128 v167, v[22:25] offset:40960
	ds_write_b128 v167, v[30:33] offset:45056
	ds_write_b128 v167, v[2:5] offset:49152
	ds_write_b128 v167, v[14:17] offset:53248
	ds_write_b128 v167, v[10:13] offset:57344
	ds_write_b128 v167, v[18:21] offset:61440
	s_waitcnt lgkmcnt(0)
	s_barrier
; __device__ __forceinline__ int tid_() { int t = threadIdx.x; asm volatile("" : "+v"(t)); return t; }
; template <int NT, bool BKN, bool MASK = false, bool ROWSS = false, class Epi> ...
;     ...
;   GEMM_COMPUTE(1);
; __device__ __forceinline__ void epi_staged_residual(f32x4 (&acc)[4][4], int r0, int c0, unsigned char* smem, const float* __restrict__ g,
;                                                     const float* __restrict__ xs, float* __restrict__ xd) {
;   constexpr int PITCH = 132;
;   float* Ts = (float*)smem;
;   const int t = tid_();
;   const int wr = r0 >> 6;
; #pragma unroll
;   for (int pass = 0; pass < 2; ++pass) {
;     __syncthreads();
;     if (wr == pass) {
; #pragma unroll
;       for (int mi = 0; mi < 4; ++mi)
; #pragma unroll
;         for (int ni = 0; ni < 4; ++ni)
; #pragma unroll
;           for (int j = 0; j < 4; ++j) Ts[((r0 & 63) + mi * 16 + j) * PITCH + c0 + ni * 16] = acc[mi][ni][j];
;     }
	ds_read_b128 v[2:5], v165 offset:32768
	ds_read_b128 v[10:13], v166 offset:49152
	s_waitcnt lgkmcnt(0)
	v_mfma_f32_16x16x32_bf16 v[14:17], v[2:5], v[10:13], v[42:45]
	ds_read_b128 v[18:21], v166 offset:51200
	ds_read_b128 v[26:29], v166 offset:53248
	s_nop 0
	ds_read_b128 v[42:45], v166 offset:55296
	s_waitcnt lgkmcnt(2)
	v_mfma_f32_16x16x32_bf16 v[22:25], v[2:5], v[18:21], v[50:53]
	s_waitcnt lgkmcnt(1)
	v_mfma_f32_16x16x32_bf16 v[30:33], v[2:5], v[26:29], v[58:61]
	s_waitcnt lgkmcnt(0)
	v_mfma_f32_16x16x32_bf16 v[2:5], v[2:5], v[42:45], v[34:37]
	s_nop 2
	ds_read_b128 v[34:37], v165 offset:34816
	v_mfma_f32_16x16x32_bf16 v[6:9], v[94:97], v[106:109], v[62:65]
	ds_read_b128 v[106:109], v164 offset:53248
	s_waitcnt lgkmcnt(1)
	v_mfma_f32_16x16x32_bf16 v[50:53], v[34:37], v[10:13], v[98:101]
	v_mfma_f32_16x16x32_bf16 v[58:61], v[34:37], v[18:21], v[102:105]
	v_mfma_f32_16x16x32_bf16 v[62:65], v[34:37], v[26:29], v[110:113]
	s_nop 1
	ds_read_b128 v[102:105], v164 offset:51200
	v_mfma_f32_16x16x32_bf16 v[34:37], v[34:37], v[42:45], v[66:69]
	ds_read_b128 v[110:113], v164 offset:55296
	s_nop 1
	ds_read_b128 v[66:69], v165 offset:36864
	v_mfma_f32_16x16x32_bf16 v[46:49], v[94:97], v[74:77], v[46:49]
	s_waitcnt lgkmcnt(0)
	v_mfma_f32_16x16x32_bf16 v[74:77], v[66:69], v[18:21], v[82:85]
	s_nop 2
	ds_read_b128 v[82:85], v165 offset:38912
	v_mfma_f32_16x16x32_bf16 v[54:57], v[94:97], v[78:81], v[54:57]
	v_mfma_f32_16x16x32_bf16 v[78:81], v[66:69], v[26:29], v[90:93]
	s_waitcnt lgkmcnt(0)
	v_mfma_f32_16x16x32_bf16 v[90:93], v[82:85], v[18:21], v[46:49]
	ds_read_b128 v[18:21], v163 offset:32768
	v_mfma_f32_16x16x32_bf16 v[38:41], v[94:97], v[70:73], v[38:41]
	v_mfma_f32_16x16x32_bf16 v[94:97], v[82:85], v[26:29], v[54:57]
	s_nop 2
	ds_read_b128 v[54:57], v164 offset:49152
	v_mfma_f32_16x16x32_bf16 v[70:73], v[66:69], v[10:13], v[114:117]
	v_mfma_f32_16x16x32_bf16 v[66:69], v[66:69], v[42:45], v[86:89]
	s_nop 1
	ds_read_b128 v[114:117], v163 offset:38912
	v_mfma_f32_16x16x32_bf16 v[86:89], v[82:85], v[10:13], v[38:41]
	v_mfma_f32_16x16x32_bf16 v[98:101], v[82:85], v[42:45], v[6:9]
	v_mov_b32_e32 v84, v187
	s_waitcnt lgkmcnt(1)
	v_mfma_f32_16x16x32_bf16 v[6:9], v[18:21], v[54:57], v[14:17]
	v_mfma_f32_16x16x32_bf16 v[14:17], v[18:21], v[102:105], v[22:25]
	v_mfma_f32_16x16x32_bf16 v[10:13], v[18:21], v[106:109], v[30:33]
	v_mfma_f32_16x16x32_bf16 v[18:21], v[18:21], v[110:113], v[2:5]
	s_nop 2
	ds_read_b128 v[2:5], v163 offset:34816
	s_waitcnt lgkmcnt(0)
	v_mfma_f32_16x16x32_bf16 v[26:29], v[2:5], v[54:57], v[50:53]
	s_nop 2
	ds_read_b128 v[50:53], v163 offset:36864
	v_mfma_f32_16x16x32_bf16 v[38:41], v[2:5], v[102:105], v[58:61]
	v_mfma_f32_16x16x32_bf16 v[22:25], v[2:5], v[106:109], v[62:65]
	v_mfma_f32_16x16x32_bf16 v[30:33], v[2:5], v[110:113], v[34:37]
	v_mad_i64_i32 v[2:3], s[8:9], s8, v0, v[136:137]
	v_lshlrev_b32_e32 v0, 2, v84
	v_and_b32_e32 v0, 0x7c, v0
	v_lshl_add_u64 v[2:3], v[2:3], 0, s[94:95]
	v_lshlrev_b32_e32 v0, 2, v0
	v_lshl_add_u64 v[2:3], v[2:3], 0, v[0:1]
	v_add_co_u32_e32 v2, vcc, 0x2000, v2
	s_waitcnt lgkmcnt(0)
	v_mfma_f32_16x16x32_bf16 v[34:37], v[50:53], v[54:57], v[70:73]
	v_addc_co_u32_e32 v3, vcc, 0, v3, vcc
	global_load_dwordx4 v[2:5], v[2:3], off
	v_mfma_f32_16x16x32_bf16 v[42:45], v[50:53], v[102:105], v[74:77]
	s_movk_i32 s8, 0x80
	v_cmp_gt_u32_e32 vcc, s8, v159
	s_waitcnt lgkmcnt(0)
	v_mfma_f32_16x16x32_bf16 v[46:49], v[50:53], v[106:109], v[78:81]
	s_barrier
	v_mfma_f32_16x16x32_bf16 v[50:53], v[50:53], v[110:113], v[66:69]
	s_nop 2
	v_mul_u32_u24_e32 v66, 0x210, v160
	v_mfma_f32_16x16x32_bf16 v[54:57], v[114:117], v[54:57], v[86:89]
	v_mfma_f32_16x16x32_bf16 v[58:61], v[114:117], v[102:105], v[90:93]
	s_nop 1
	v_lshlrev_b32_e32 v87, 2, v66
	v_lshl_or_b32 v86, v161, 6, v162
	v_mfma_f32_16x16x32_bf16 v[62:65], v[114:117], v[106:109], v[94:97]
	v_mfma_f32_16x16x32_bf16 v[66:69], v[114:117], v[110:113], v[98:101]
	s_and_saveexec_b64 s[8:9], vcc
	s_cbranch_execz .LBB0_849
	v_lshl_add_u32 v70, v86, 2, v87
	v_add_u32_e32 v71, 0x400, v70
	ds_write2_b32 v70, v6, v14 offset1:16
	ds_write2_b32 v70, v7, v15 offset0:132 offset1:148
	ds_write2_b32 v71, v8, v16 offset0:8 offset1:24
	ds_write2_b32 v71, v9, v17 offset0:140 offset1:156
	ds_write2_b32 v70, v10, v18 offset0:32 offset1:48
	ds_write2_b32 v70, v11, v19 offset0:164 offset1:180
	ds_write2_b32 v71, v12, v20 offset0:40 offset1:56
	ds_write2_b32 v71, v13, v21 offset0:172 offset1:188
	v_add_u32_e32 v71, 0x2000, v70
	v_add_u32_e32 v72, 0x2400, v70
	ds_write2_b32 v71, v26, v38 offset0:64 offset1:80
	ds_write2_b32 v71, v27, v39 offset0:196 offset1:212
	ds_write2_b32 v72, v28, v40 offset0:72 offset1:88
	ds_write2_b32 v72, v29, v41 offset0:204 offset1:220
	ds_write2_b32 v71, v22, v30 offset0:96 offset1:112
	ds_write2_b32 v71, v23, v31 offset0:228 offset1:244
	ds_write2_b32 v72, v24, v32 offset0:104 offset1:120
	ds_write2_b32 v72, v25, v33 offset0:236 offset1:252
	v_add_u32_e32 v71, 0x4000, v70
	v_add_u32_e32 v72, 0x4400, v70
	v_add_u32_e32 v73, 0x4800, v70
	ds_write2_b32 v71, v34, v42 offset0:128 offset1:144
	ds_write2_b32 v72, v35, v43 offset0:4 offset1:20
	ds_write2_b32 v72, v36, v44 offset0:136 offset1:152
	ds_write2_b32 v73, v37, v45 offset0:12 offset1:28
	ds_write2_b32 v71, v46, v50 offset0:160 offset1:176
	ds_write2_b32 v72, v47, v51 offset0:36 offset1:52
	ds_write2_b32 v72, v48, v52 offset0:168 offset1:184
	ds_write2_b32 v73, v49, v53 offset0:44 offset1:60
	v_add_u32_e32 v71, 0x6000, v70
	v_add_u32_e32 v72, 0x6400, v70
	v_add_u32_e32 v70, 0x6800, v70
	ds_write2_b32 v71, v54, v58 offset0:192 offset1:208
	ds_write2_b32 v72, v55, v59 offset0:68 offset1:84
	ds_write2_b32 v72, v56, v60 offset0:200 offset1:216
	ds_write2_b32 v70, v57, v61 offset0:76 offset1:92
	ds_write2_b32 v71, v62, v66 offset0:224 offset1:240
	ds_write2_b32 v72, v63, v67 offset0:100 offset1:116
	ds_write2_b32 v72, v64, v68 offset0:232 offset1:248
	ds_write2_b32 v70, v65, v69 offset0:108 offset1:124

; template <int NT, bool BKN, bool MASK = false, bool ROWSS = false, class Epi> ...
;     ...
;   float ss_[4] = {0.f, 0.f, 0.f, 0.f};
;   int stk_ = 0;
;   f32x4 acc[4][NT];
; #pragma unroll
;   for (int i = 0; i < 4; ++i)
; #pragma unroll
;     for (int j = 0; j < NT; ++j) acc[i][j] = (f32x4){0.f, 0.f, 0.f, 0.f};
;   const int nk = K >> 6;
;   const int nkm1 = nk - 1;
;   __syncthreads();
;   GEMM_LOAD(ra0, rb0, 0);
;   GEMM_LOAD(ra1, rb1, 1);
;   GEMM_STORE(ra0, rb0, 0);
;   GEMM_LOAD(ra0, rb0, (2 < nkm1 ? 2 : nkm1));
;   __syncthreads();
;   for (int kt = 0; kt < nk - 2; kt += 2) {
;     GEMM_COMPUTE(0);
;     GEMM_STORE(ra1, rb1, 1);
;     GEMM_LOAD(ra1, rb1, kt + 3);
;     __syncthreads();
;     GEMM_COMPUTE(1);
;     GEMM_STORE(ra0, rb0, 0);
;     GEMM_LOAD(ra0, rb0, (kt + 4 < nkm1 ? kt + 4 : nkm1));
;     __syncthreads();
;   }
.LBB0_1162:
	s_add_i32 s0, s0, 2
	s_min_u32 s1, s0, 11
	s_lshl_b32 s94, s1, 7
	s_cmp_lt_u32 s0, 12
	s_waitcnt lgkmcnt(3)
	v_mfma_f32_16x16x32_bf16 v[78:81], v[158:161], v[188:191], v[78:81]
	v_mfma_f32_16x16x32_bf16 v[74:77], v[158:161], v[192:195], v[74:77]
	v_mfma_f32_16x16x32_bf16 v[66:69], v[158:161], v[196:199], v[66:69]
	v_mfma_f32_16x16x32_bf16 v[70:73], v[158:161], v[200:203], v[70:73]
	ds_read_b128 v[230:233], v167
	ds_read_b128 v[204:207], v166 offset:16384
	ds_read_b128 v[208:211], v166 offset:18432
	ds_read_b128 v[216:219], v166 offset:20480
	ds_read_b128 v[220:223], v166 offset:22528
	s_waitcnt lgkmcnt(7)
	v_mfma_f32_16x16x32_bf16 v[90:93], v[172:175], v[188:191], v[90:93]
	v_mfma_f32_16x16x32_bf16 v[86:89], v[172:175], v[192:195], v[86:89]
	v_mfma_f32_16x16x32_bf16 v[82:85], v[172:175], v[196:199], v[82:85]
	v_mfma_f32_16x16x32_bf16 v[114:117], v[172:175], v[200:203], v[114:117]
	s_waitcnt lgkmcnt(6)
	v_mfma_f32_16x16x32_bf16 v[102:105], v[176:179], v[188:191], v[102:105]
	v_mfma_f32_16x16x32_bf16 v[110:113], v[176:179], v[192:195], v[110:113]
	v_mfma_f32_16x16x32_bf16 v[106:109], v[176:179], v[196:199], v[106:109]
	v_mfma_f32_16x16x32_bf16 v[98:101], v[176:179], v[200:203], v[98:101]
	ds_read_b128 v[242:245], v167 offset:2048
	ds_read_b128 v[234:237], v167 offset:4096
	ds_read_b128 v[238:241], v167 offset:6144
	s_waitcnt lgkmcnt(8)
	v_mfma_f32_16x16x32_bf16 v[94:97], v[180:183], v[188:191], v[94:97]
	v_mfma_f32_16x16x32_bf16 v[126:129], v[180:183], v[192:195], v[126:129]
	v_mfma_f32_16x16x32_bf16 v[122:125], v[180:183], v[196:199], v[122:125]
	v_mfma_f32_16x16x32_bf16 v[118:121], v[180:183], v[200:203], v[118:121]
	s_waitcnt lgkmcnt(3)
	v_mfma_f32_16x16x32_bf16 v[78:81], v[230:233], v[204:207], v[78:81]
	s_waitcnt vmcnt(8)
	ds_write_b128 v170, v[14:17] offset:32768
	ds_write_b128 v170, v[10:13] offset:36864
	ds_write_b128 v170, v[6:9] offset:40960
	ds_write_b128 v170, v[18:21] offset:45056
	v_mfma_f32_16x16x32_bf16 v[74:77], v[230:233], v[208:211], v[74:77]
	ds_write_b128 v170, v[2:5] offset:49152
	ds_write_b128 v170, v[30:33] offset:53248
	ds_write_b128 v170, v[22:25] offset:57344
	ds_write_b128 v170, v[26:29] offset:61440
	v_mfma_f32_16x16x32_bf16 v[66:69], v[230:233], v[216:219], v[66:69]
	v_lshl_add_u64 v[2:3], v[156:157], 0, v[0:1]
	v_lshl_add_u64 v[4:5], v[154:155], 0, v[0:1]
	v_lshl_add_u64 v[6:7], v[152:153], 0, v[0:1]
	v_lshl_add_u64 v[18:19], v[150:151], 0, v[0:1]
	v_mfma_f32_16x16x32_bf16 v[70:73], v[230:233], v[220:223], v[70:73]
	v_lshl_add_u64 v[22:23], v[148:149], 0, v[0:1]
	v_lshl_add_u64 v[24:25], v[146:147], 0, v[0:1]
	global_load_dwordx4 v[14:17], v[2:3], off
	global_load_dwordx4 v[10:13], v[4:5], off
	s_waitcnt lgkmcnt(10)
	v_mfma_f32_16x16x32_bf16 v[90:93], v[242:245], v[204:207], v[90:93]
	s_nop 0
	global_load_dwordx4 v[6:9], v[6:7], off
	s_nop 0
	global_load_dwordx4 v[18:21], v[18:19], off
	s_nop 0
	global_load_dwordx4 v[2:5], v[22:23], off
	v_add_co_u32_e32 v22, vcc, s15, v24
	v_mfma_f32_16x16x32_bf16 v[86:89], v[242:245], v[208:211], v[86:89]
	v_addc_co_u32_e32 v23, vcc, 0, v25, vcc
	v_add_co_u32_e32 v26, vcc, s16, v24
	v_addc_co_u32_e32 v27, vcc, 0, v25, vcc
	v_add_co_u32_e32 v28, vcc, s17, v24
	v_mfma_f32_16x16x32_bf16 v[82:85], v[242:245], v[216:219], v[82:85]
	v_addc_co_u32_e32 v29, vcc, 0, v25, vcc
	global_load_dwordx4 v[30:33], v[22:23], off offset:384
	s_nop 0
	global_load_dwordx4 v[22:25], v[26:27], off offset:384
	s_nop 0
	global_load_dwordx4 v[26:29], v[28:29], off offset:384
	v_mfma_f32_16x16x32_bf16 v[114:117], v[242:245], v[220:223], v[114:117]
	s_waitcnt lgkmcnt(0)
	s_barrier
	ds_read_b128 v[158:161], v169 offset:32768
	ds_read_b128 v[188:191], v168 offset:49152
	ds_read_b128 v[192:195], v168 offset:51200
	ds_read_b128 v[196:199], v168 offset:53248
	ds_read_b128 v[200:203], v168 offset:55296
	ds_read_b128 v[172:175], v169 offset:34816
	ds_read_b128 v[176:179], v169 offset:36864
	ds_read_b128 v[180:183], v169 offset:38912
	v_mfma_f32_16x16x32_bf16 v[102:105], v[234:237], v[204:207], v[102:105]
	v_mfma_f32_16x16x32_bf16 v[110:113], v[234:237], v[208:211], v[110:113]
	v_mfma_f32_16x16x32_bf16 v[106:109], v[234:237], v[216:219], v[106:109]
	v_mfma_f32_16x16x32_bf16 v[98:101], v[234:237], v[220:223], v[98:101]
	v_mfma_f32_16x16x32_bf16 v[94:97], v[238:241], v[204:207], v[94:97]
	v_mfma_f32_16x16x32_bf16 v[126:129], v[238:241], v[208:211], v[126:129]
	v_mfma_f32_16x16x32_bf16 v[122:125], v[238:241], v[216:219], v[122:125]
	v_mfma_f32_16x16x32_bf16 v[118:121], v[238:241], v[220:223], v[118:121]
	s_waitcnt lgkmcnt(3)
	v_mfma_f32_16x16x32_bf16 v[78:81], v[158:161], v[188:191], v[78:81]
	v_mfma_f32_16x16x32_bf16 v[74:77], v[158:161], v[192:195], v[74:77]
	v_mfma_f32_16x16x32_bf16 v[66:69], v[158:161], v[196:199], v[66:69]
	v_mfma_f32_16x16x32_bf16 v[70:73], v[158:161], v[200:203], v[70:73]
	ds_read_b128 v[230:233], v167 offset:32768
	ds_read_b128 v[204:207], v166 offset:49152
	ds_read_b128 v[208:211], v166 offset:51200
	ds_read_b128 v[216:219], v166 offset:53248
	ds_read_b128 v[220:223], v166 offset:55296
	s_waitcnt lgkmcnt(7)
	v_mfma_f32_16x16x32_bf16 v[90:93], v[172:175], v[188:191], v[90:93]
	v_mfma_f32_16x16x32_bf16 v[86:89], v[172:175], v[192:195], v[86:89]
	v_mfma_f32_16x16x32_bf16 v[82:85], v[172:175], v[196:199], v[82:85]
	v_mfma_f32_16x16x32_bf16 v[114:117], v[172:175], v[200:203], v[114:117]
	s_waitcnt lgkmcnt(6)
	v_mfma_f32_16x16x32_bf16 v[102:105], v[176:179], v[188:191], v[102:105]
	v_mfma_f32_16x16x32_bf16 v[110:113], v[176:179], v[192:195], v[110:113]
	v_mfma_f32_16x16x32_bf16 v[106:109], v[176:179], v[196:199], v[106:109]
	v_mfma_f32_16x16x32_bf16 v[98:101], v[176:179], v[200:203], v[98:101]
	ds_read_b128 v[242:245], v167 offset:34816
	ds_read_b128 v[234:237], v167 offset:36864
	ds_read_b128 v[238:241], v167 offset:38912
	s_waitcnt lgkmcnt(8)
; template <int NT, bool BKN, bool MASK = false, bool ROWSS = false, class Epi> ...
;     ...
;   for (int kt = 0; kt < nk - 2; kt += 2) {
;     GEMM_COMPUTE(0);
;     GEMM_STORE(ra1, rb1, 1);
;     GEMM_LOAD(ra1, rb1, kt + 3);
;     __syncthreads();
;     GEMM_COMPUTE(1);
;     GEMM_STORE(ra0, rb0, 0);
;     GEMM_LOAD(ra0, rb0, (kt + 4 < nkm1 ? kt + 4 : nkm1));
;     __syncthreads();
;   }
;   GEMM_COMPUTE(0);
;   GEMM_STORE(ra1, rb1, 1);
;   __syncthreads();
	v_mfma_f32_16x16x32_bf16 v[94:97], v[180:183], v[188:191], v[94:97]
	v_mfma_f32_16x16x32_bf16 v[126:129], v[180:183], v[192:195], v[126:129]
	v_mfma_f32_16x16x32_bf16 v[122:125], v[180:183], v[196:199], v[122:125]
	v_mfma_f32_16x16x32_bf16 v[118:121], v[180:183], v[200:203], v[118:121]
	s_waitcnt lgkmcnt(3)
	v_mfma_f32_16x16x32_bf16 v[78:81], v[230:233], v[204:207], v[78:81]
	v_lshl_add_u64 v[146:147], v[146:147], 0, s[6:7]
	v_lshl_add_u64 v[148:149], v[148:149], 0, s[6:7]
	v_lshl_add_u64 v[150:151], v[150:151], 0, s[6:7]
	v_lshl_add_u64 v[152:153], v[152:153], 0, s[6:7]
	v_mfma_f32_16x16x32_bf16 v[74:77], v[230:233], v[208:211], v[74:77]
	v_lshl_add_u64 v[154:155], v[154:155], 0, s[6:7]
	v_lshl_add_u64 v[156:157], v[156:157], 0, s[6:7]
	s_waitcnt vmcnt(8)
	ds_write_b128 v170, v[34:37]
	ds_write_b128 v170, v[38:41] offset:4096
	v_mfma_f32_16x16x32_bf16 v[66:69], v[230:233], v[216:219], v[66:69]
	ds_write_b128 v170, v[42:45] offset:8192
	ds_write_b128 v170, v[46:49] offset:12288
	ds_write_b128 v170, v[50:53] offset:16384
	ds_write_b128 v170, v[58:61] offset:20480
	v_mfma_f32_16x16x32_bf16 v[70:73], v[230:233], v[220:223], v[70:73]
	ds_write_b128 v170, v[54:57] offset:24576
	ds_write_b128 v170, v[62:65] offset:28672
	v_lshl_add_u64 v[34:35], v[134:135], 0, s[94:95]
	v_lshl_add_u64 v[38:39], v[132:133], 0, s[94:95]
	s_waitcnt lgkmcnt(10)
	v_mfma_f32_16x16x32_bf16 v[90:93], v[242:245], v[204:207], v[90:93]
	v_lshl_add_u64 v[42:43], v[130:131], 0, s[94:95]
	v_lshl_add_u64 v[46:47], v[136:137], 0, s[94:95]
	v_lshl_add_u64 v[50:51], v[138:139], 0, s[94:95]
	v_lshl_add_u64 v[54:55], v[140:141], 0, s[94:95]
	v_mfma_f32_16x16x32_bf16 v[86:89], v[242:245], v[208:211], v[86:89]
	v_lshl_add_u64 v[56:57], v[142:143], 0, s[94:95]
	v_lshl_add_u64 v[62:63], v[144:145], 0, s[94:95]
	v_mfma_f32_16x16x32_bf16 v[82:85], v[242:245], v[216:219], v[82:85]
	s_nop 0
	v_mfma_f32_16x16x32_bf16 v[114:117], v[242:245], v[220:223], v[114:117]
	s_nop 0
	s_cbranch_scc0 .Lgd_lbb0_1162
	global_load_dwordx4 v[34:37], v[34:35], off offset:512
	s_nop 0
	global_load_dwordx4 v[38:41], v[38:39], off offset:512
	s_nop 0
	global_load_dwordx4 v[42:45], v[42:43], off offset:512
	s_nop 0
	global_load_dwordx4 v[46:49], v[46:47], off offset:512
	s_nop 0
	global_load_dwordx4 v[50:53], v[50:51], off offset:512
	s_nop 0
	global_load_dwordx4 v[58:61], v[54:55], off offset:512
	s_nop 0
	global_load_dwordx4 v[54:57], v[56:57], off offset:512
	s_nop 0
	global_load_dwordx4 v[62:65], v[62:63], off offset:512
	s_nop 0
.Lgd_lbb0_1162:
	s_waitcnt lgkmcnt(0)
	s_barrier
	ds_read_b128 v[158:161], v169
	ds_read_b128 v[188:191], v168 offset:16384
	ds_read_b128 v[192:195], v168 offset:18432
	ds_read_b128 v[196:199], v168 offset:20480
	ds_read_b128 v[200:203], v168 offset:22528
	ds_read_b128 v[172:175], v169 offset:2048
	ds_read_b128 v[176:179], v169 offset:4096
	ds_read_b128 v[180:183], v169 offset:6144
	v_mfma_f32_16x16x32_bf16 v[102:105], v[234:237], v[204:207], v[102:105]
	v_mfma_f32_16x16x32_bf16 v[110:113], v[234:237], v[208:211], v[110:113]
	v_mfma_f32_16x16x32_bf16 v[106:109], v[234:237], v[216:219], v[106:109]
	v_mfma_f32_16x16x32_bf16 v[98:101], v[234:237], v[220:223], v[98:101]
	v_mfma_f32_16x16x32_bf16 v[94:97], v[238:241], v[204:207], v[94:97]
	v_mfma_f32_16x16x32_bf16 v[126:129], v[238:241], v[208:211], v[126:129]
	v_mfma_f32_16x16x32_bf16 v[122:125], v[238:241], v[216:219], v[122:125]
	v_mfma_f32_16x16x32_bf16 v[118:121], v[238:241], v[220:223], v[118:121]
	s_cbranch_scc1 .LBB0_1162
	s_waitcnt vmcnt(0)
	ds_read_b128 v[34:37], v169
	ds_read_b128 v[38:41], v169 offset:2048
	ds_read_b128 v[42:45], v169 offset:4096
	ds_read_b128 v[46:49], v169 offset:6144
	ds_read_b128 v[50:53], v168 offset:16384
	ds_read_b128 v[54:57], v168 offset:18432
	ds_read_b128 v[58:61], v168 offset:20480
	ds_read_b128 v[62:65], v168 offset:22528
	v_lshlrev_b32_e32 v0, 6, v164
	s_waitcnt lgkmcnt(3)
	v_mfma_f32_16x16x32_bf16 v[78:81], v[34:37], v[50:53], v[78:81]
	v_lshl_or_b32 v0, v165, 2, v0
	v_mul_lo_u32 v0, v0, s96
	s_waitcnt lgkmcnt(2)
	v_mfma_f32_16x16x32_bf16 v[74:77], v[34:37], v[54:57], v[74:77]
	s_waitcnt lgkmcnt(1)
	v_mfma_f32_16x16x32_bf16 v[66:69], v[34:37], v[58:61], v[66:69]
	s_waitcnt lgkmcnt(0)
	v_mfma_f32_16x16x32_bf16 v[34:37], v[34:37], v[62:65], v[70:73]
	v_mfma_f32_16x16x32_bf16 v[70:73], v[38:41], v[50:53], v[90:93]
	v_mfma_f32_16x16x32_bf16 v[86:89], v[38:41], v[54:57], v[86:89]
	v_mfma_f32_16x16x32_bf16 v[82:85], v[38:41], v[58:61], v[82:85]
	v_mfma_f32_16x16x32_bf16 v[38:41], v[38:41], v[62:65], v[114:117]
	v_mfma_f32_16x16x32_bf16 v[90:93], v[42:45], v[50:53], v[102:105]
	v_mfma_f32_16x16x32_bf16 v[102:105], v[42:45], v[54:57], v[110:113]
	v_mfma_f32_16x16x32_bf16 v[106:109], v[42:45], v[58:61], v[106:109]
	v_mfma_f32_16x16x32_bf16 v[42:45], v[42:45], v[62:65], v[98:101]
	v_mfma_f32_16x16x32_bf16 v[50:53], v[46:49], v[50:53], v[94:97]
	v_mfma_f32_16x16x32_bf16 v[54:57], v[46:49], v[54:57], v[126:129]
	v_mfma_f32_16x16x32_bf16 v[58:61], v[46:49], v[58:61], v[122:125]
	v_mfma_f32_16x16x32_bf16 v[46:49], v[46:49], v[62:65], v[118:121]
	ds_read_b128 v[62:65], v167
	ds_read_b128 v[94:97], v167 offset:2048
	ds_read_b128 v[98:101], v167 offset:4096
	ds_read_b128 v[110:113], v167 offset:6144
	ds_read_b128 v[114:117], v166 offset:16384
	ds_read_b128 v[118:121], v166 offset:18432
	ds_read_b128 v[122:125], v166 offset:20480
	ds_read_b128 v[126:129], v166 offset:22528
	ds_write_b128 v170, v[14:17] offset:32768
	ds_write_b128 v170, v[10:13] offset:36864
	ds_write_b128 v170, v[6:9] offset:40960
	ds_write_b128 v170, v[18:21] offset:45056
	ds_write_b128 v170, v[2:5] offset:49152
	ds_write_b128 v170, v[30:33] offset:53248
	ds_write_b128 v170, v[22:25] offset:57344
	ds_write_b128 v170, v[26:29] offset:61440
	s_waitcnt lgkmcnt(0)
	v_mfma_f32_16x16x32_bf16 v[78:81], v[62:65], v[114:117], v[78:81]
	s_barrier
; __device__ __forceinline__ u16 f2bf(float f) { return (u16)(pack2(f, 0.f) & 0xffffu); }
; __device__ __forceinline__ int tid_() { int t = threadIdx.x; asm volatile("" : "+v"(t)); return t; }
; __device__ __forceinline__ float silu_f(float x) { return x / (1.f + __expf(-x)); }
; template <int NT, bool BKN, bool MASK = false, bool ROWSS = false, class Epi> ...
;     ...
;   GEMM_COMPUTE(0);
;   GEMM_STORE(ra1, rb1, 1);
;   __syncthreads();
;   GEMM_COMPUTE(1);
; __device__ __forceinline__ void phase_moe_up(const Params& p, int l, bool last, unsigned char* smem) {
;     ...
;     auto epi = [&](f32x4(&acc)[4][4], int r0, int c0) {
;       u16* Ts = (u16*)smem;
;       const int t2 = tid_();
;       __syncthreads();
; #pragma unroll
;       for (int mi = 0; mi < 4; ++mi)
; #pragma unroll
;         for (int n2 = 0; n2 < 2; ++n2)
; #pragma unroll
;           for (int j = 0; j < 4; ++j) {
;             const int m = r0 + mi * 16 + j;
;             const int fl = (c0 >> 6) * 32 + n2 * 16 + (c0 & 15);
;             Ts[m * 72 + fl] = f2bf(silu_f(acc[mi][2 * n2][j]) * acc[mi][2 * n2 + 1][j]);
;           }
	ds_read_b128 v[2:5], v169 offset:32768
	ds_read_b128 v[6:9], v169 offset:34816
	ds_read_b128 v[10:13], v169 offset:36864
	ds_read_b128 v[14:17], v169 offset:38912
	ds_read_b128 v[18:21], v168 offset:49152
	ds_read_b128 v[22:25], v168 offset:51200
	ds_read_b128 v[26:29], v168 offset:53248
	ds_read_b128 v[30:33], v168 offset:55296
	v_mfma_f32_16x16x32_bf16 v[74:77], v[62:65], v[118:121], v[74:77]
	v_mfma_f32_16x16x32_bf16 v[66:69], v[62:65], v[122:125], v[66:69]
	v_mfma_f32_16x16x32_bf16 v[34:37], v[62:65], v[126:129], v[34:37]
	v_mfma_f32_16x16x32_bf16 v[62:65], v[94:97], v[114:117], v[70:73]
	v_mfma_f32_16x16x32_bf16 v[70:73], v[94:97], v[118:121], v[86:89]
	v_mfma_f32_16x16x32_bf16 v[86:89], v[98:101], v[114:117], v[90:93]
	v_mfma_f32_16x16x32_bf16 v[90:93], v[98:101], v[118:121], v[102:105]
	v_mfma_f32_16x16x32_bf16 v[50:53], v[110:113], v[114:117], v[50:53]
	v_mfma_f32_16x16x32_bf16 v[54:57], v[110:113], v[118:121], v[54:57]
	v_mfma_f32_16x16x32_bf16 v[58:61], v[110:113], v[122:125], v[58:61]
	v_mfma_f32_16x16x32_bf16 v[46:49], v[110:113], v[126:129], v[46:49]
	s_waitcnt lgkmcnt(3)
	v_mfma_f32_16x16x32_bf16 v[78:81], v[2:5], v[18:21], v[78:81]
	v_mfma_f32_16x16x32_bf16 v[82:85], v[94:97], v[122:125], v[82:85]
	v_mfma_f32_16x16x32_bf16 v[38:41], v[94:97], v[126:129], v[38:41]
	v_mfma_f32_16x16x32_bf16 v[94:97], v[98:101], v[122:125], v[106:109]
	v_mfma_f32_16x16x32_bf16 v[42:45], v[98:101], v[126:129], v[42:45]
	s_waitcnt lgkmcnt(2)
	v_mfma_f32_16x16x32_bf16 v[74:77], v[2:5], v[22:25], v[74:77]
	s_waitcnt lgkmcnt(1)
	v_mfma_f32_16x16x32_bf16 v[66:69], v[2:5], v[26:29], v[66:69]
	s_waitcnt lgkmcnt(0)
	v_mfma_f32_16x16x32_bf16 v[2:5], v[2:5], v[30:33], v[34:37]
	v_mfma_f32_16x16x32_bf16 v[34:37], v[6:9], v[18:21], v[62:65]
	v_mfma_f32_16x16x32_bf16 v[70:73], v[6:9], v[22:25], v[70:73]
	v_mfma_f32_16x16x32_bf16 v[86:89], v[10:13], v[18:21], v[86:89]
	v_mfma_f32_16x16x32_bf16 v[90:93], v[10:13], v[22:25], v[90:93]
	v_mfma_f32_16x16x32_bf16 v[98:101], v[14:17], v[18:21], v[50:53]
	v_mfma_f32_16x16x32_bf16 v[102:105], v[14:17], v[22:25], v[54:57]
	v_mfma_f32_16x16x32_bf16 v[106:109], v[14:17], v[26:29], v[58:61]
	v_mfma_f32_16x16x32_bf16 v[110:113], v[14:17], v[30:33], v[46:49]
	ds_read_b128 v[14:17], v167 offset:32768
	ds_read_b128 v[18:21], v167 offset:34816
	ds_read_b128 v[22:25], v167 offset:36864
	ds_read_b128 v[114:117], v167 offset:38912
	ds_read_b128 v[118:121], v166 offset:49152
	ds_read_b128 v[122:125], v166 offset:51200
	ds_read_b128 v[126:129], v166 offset:53248
	ds_read_b128 v[130:133], v166 offset:55296
	s_waitcnt lgkmcnt(3)
	v_mfma_f32_16x16x32_bf16 v[58:61], v[14:17], v[118:121], v[78:81]
	s_waitcnt lgkmcnt(1)
	v_mfma_f32_16x16x32_bf16 v[50:53], v[14:17], v[126:129], v[66:69]
	v_mfma_f32_16x16x32_bf16 v[46:49], v[18:21], v[122:125], v[70:73]
	s_nop 4
	v_mul_f32_e32 v68, 0xbfb8aa3b, v58
	v_exp_f32_e32 v68, v68
	v_lshlrev_b32_e32 v67, 5, v163
	v_mfma_f32_16x16x32_bf16 v[62:65], v[14:17], v[122:125], v[74:77]
	v_and_or_b32 v67, v67, 32, v162
	v_add_f32_e32 v68, 1.0, v68
	v_div_scale_f32 v69, s[0:1], v68, v68, v58
	v_rcp_f32_e32 v70, v69
	v_mov_b32_e32 v66, v187
	v_lshl_add_u32 v0, v67, 1, v0
	v_fma_f32 v71, -v69, v70, 1.0
	v_fmac_f32_e32 v70, v71, v70
	v_div_scale_f32 v71, vcc, v58, v68, v58
	v_mul_f32_e32 v72, v71, v70
	v_fma_f32 v73, -v69, v72, v71
	v_fmac_f32_e32 v72, v73, v70
	v_fma_f32 v69, -v69, v72, v71
	v_div_fmas_f32 v69, v69, v70, v72
	v_div_fixup_f32 v58, v69, v68, v58
	v_mul_f32_e32 v58, v62, v58
	v_cvt_pk_bf16_f32 v58, v58, s0
	s_waitcnt lgkmcnt(0)
	s_barrier
	ds_write_b16 v0, v58
	v_mul_f32_e32 v58, 0xbfb8aa3b, v59
	v_exp_f32_e32 v58, v58
	v_mfma_f32_16x16x32_bf16 v[54:57], v[14:17], v[130:133], v[2:5]
	v_add_f32_e32 v58, 1.0, v58
	v_div_scale_f32 v62, s[0:1], v58, v58, v59
	v_rcp_f32_e32 v67, v62
	v_mfma_f32_16x16x32_bf16 v[94:97], v[10:13], v[26:29], v[94:97]
	v_fma_f32 v68, -v62, v67, 1.0
	v_fmac_f32_e32 v67, v68, v67
	v_div_scale_f32 v68, vcc, v59, v58, v59
	v_mul_f32_e32 v69, v68, v67
	v_fma_f32 v70, -v62, v69, v68
	v_fmac_f32_e32 v69, v70, v67
	v_fma_f32 v62, -v62, v69, v68
	v_div_fmas_f32 v62, v62, v67, v69
	v_div_fixup_f32 v58, v62, v58, v59
	v_mul_f32_e32 v58, v63, v58
	v_cvt_pk_bf16_f32 v58, v58, s0
	ds_write_b16 v0, v58 offset:144
	v_mul_f32_e32 v58, 0xbfb8aa3b, v60
	v_exp_f32_e32 v58, v58
	v_mfma_f32_16x16x32_bf16 v[10:13], v[10:13], v[30:33], v[42:45]
	v_add_f32_e32 v58, 1.0, v58
	v_div_scale_f32 v59, s[0:1], v58, v58, v60
	v_rcp_f32_e32 v62, v59
	v_mfma_f32_16x16x32_bf16 v[42:45], v[18:21], v[118:121], v[34:37]
	v_fma_f32 v63, -v59, v62, 1.0
	v_fmac_f32_e32 v62, v63, v62
	v_div_scale_f32 v63, vcc, v60, v58, v60
	v_mul_f32_e32 v67, v63, v62
	v_fma_f32 v68, -v59, v67, v63
	v_fmac_f32_e32 v67, v68, v62
	v_fma_f32 v59, -v59, v67, v63
	v_div_fmas_f32 v59, v59, v62, v67
	v_div_fixup_f32 v58, v59, v58, v60
	v_mul_f32_e32 v58, v64, v58
	v_cvt_pk_bf16_f32 v58, v58, s0
	ds_write_b16 v0, v58 offset:288
	v_mul_f32_e32 v58, 0xbfb8aa3b, v61
	v_exp_f32_e32 v58, v58
	v_mfma_f32_16x16x32_bf16 v[82:85], v[6:9], v[26:29], v[82:85]
	v_add_f32_e32 v58, 1.0, v58
	v_div_scale_f32 v59, s[0:1], v58, v58, v61
	v_rcp_f32_e32 v60, v59
	v_mfma_f32_16x16x32_bf16 v[34:37], v[18:21], v[126:129], v[82:85]
	v_fma_f32 v62, -v59, v60, 1.0
	v_fmac_f32_e32 v60, v62, v60
	v_div_scale_f32 v62, vcc, v61, v58, v61
	v_mul_f32_e32 v63, v62, v60
	v_fma_f32 v64, -v59, v63, v62
	v_fmac_f32_e32 v63, v64, v60
	v_fma_f32 v59, -v59, v63, v62
	v_div_fmas_f32 v59, v59, v60, v63
	v_div_fixup_f32 v58, v59, v58, v61
	v_mul_f32_e32 v58, v65, v58
	v_cvt_pk_bf16_f32 v58, v58, s0
	ds_write_b16 v0, v58 offset:432
	v_mul_f32_e32 v58, 0xbfb8aa3b, v50
; __device__ __forceinline__ u16 f2bf(float f) { return (u16)(pack2(f, 0.f) & 0xffffu); }
; __device__ __forceinline__ float silu_f(float x) { return x / (1.f + __expf(-x)); }
; __device__ __forceinline__ void phase_moe_up(const Params& p, int l, bool last, unsigned char* smem) {
;     ...
; #pragma unroll
;       for (int mi = 0; mi < 4; ++mi)
; #pragma unroll
;         for (int n2 = 0; n2 < 2; ++n2)
; #pragma unroll
;           for (int j = 0; j < 4; ++j) {
;             const int m = r0 + mi * 16 + j;
;             const int fl = (c0 >> 6) * 32 + n2 * 16 + (c0 & 15);
;             Ts[m * 72 + fl] = f2bf(silu_f(acc[mi][2 * n2][j]) * acc[mi][2 * n2 + 1][j]);
;           }
	v_exp_f32_e32 v58, v58
	v_mfma_f32_16x16x32_bf16 v[6:9], v[6:9], v[30:33], v[38:41]
	v_add_f32_e32 v58, 1.0, v58
	v_div_scale_f32 v59, s[0:1], v58, v58, v50
	v_rcp_f32_e32 v60, v59
	v_mfma_f32_16x16x32_bf16 v[38:41], v[18:21], v[130:133], v[6:9]
	v_fma_f32 v61, -v59, v60, 1.0
	v_fmac_f32_e32 v60, v61, v60
	v_div_scale_f32 v61, vcc, v50, v58, v50
	v_mul_f32_e32 v62, v61, v60
	v_fma_f32 v63, -v59, v62, v61
	v_fmac_f32_e32 v62, v63, v60
	v_fma_f32 v59, -v59, v62, v61
	v_div_fmas_f32 v59, v59, v60, v62
	v_div_fixup_f32 v50, v59, v58, v50
	v_mul_f32_e32 v50, v54, v50
	v_cvt_pk_bf16_f32 v50, v50, s0
	ds_write_b16 v0, v50 offset:32
	v_mul_f32_e32 v50, 0xbfb8aa3b, v51
	v_exp_f32_e32 v50, v50
	v_mfma_f32_16x16x32_bf16 v[26:29], v[22:25], v[118:121], v[86:89]
	v_add_f32_e32 v50, 1.0, v50
	v_div_scale_f32 v54, s[0:1], v50, v50, v51
	v_rcp_f32_e32 v58, v54
	v_mfma_f32_16x16x32_bf16 v[30:33], v[22:25], v[122:125], v[90:93]
	v_fma_f32 v59, -v54, v58, 1.0
	v_fmac_f32_e32 v58, v59, v58
	v_div_scale_f32 v59, vcc, v51, v50, v51
	v_mul_f32_e32 v60, v59, v58
	v_fma_f32 v61, -v54, v60, v59
	v_fmac_f32_e32 v60, v61, v58
	v_fma_f32 v54, -v54, v60, v59
	v_div_fmas_f32 v54, v54, v58, v60
	v_div_fixup_f32 v50, v54, v50, v51
	v_mul_f32_e32 v50, v55, v50
	v_cvt_pk_bf16_f32 v50, v50, s0
	ds_write_b16 v0, v50 offset:176
	v_mul_f32_e32 v50, 0xbfb8aa3b, v52
	v_exp_f32_e32 v50, v50
	v_mfma_f32_16x16x32_bf16 v[18:21], v[22:25], v[126:129], v[94:97]
	v_add_f32_e32 v50, 1.0, v50
	v_div_scale_f32 v51, s[0:1], v50, v50, v52
	v_rcp_f32_e32 v54, v51
	v_mfma_f32_16x16x32_bf16 v[22:25], v[22:25], v[130:133], v[10:13]
	v_fma_f32 v55, -v51, v54, 1.0
	v_fmac_f32_e32 v54, v55, v54
	v_div_scale_f32 v55, vcc, v52, v50, v52
	v_mul_f32_e32 v58, v55, v54
	v_fma_f32 v59, -v51, v58, v55
	v_fmac_f32_e32 v58, v59, v54
	v_fma_f32 v51, -v51, v58, v55
	v_div_fmas_f32 v51, v51, v54, v58
	v_div_fixup_f32 v50, v51, v50, v52
	v_mul_f32_e32 v50, v56, v50
	v_cvt_pk_bf16_f32 v50, v50, s0
	ds_write_b16 v0, v50 offset:320
	v_mul_f32_e32 v50, 0xbfb8aa3b, v53
	v_exp_f32_e32 v50, v50
	v_mfma_f32_16x16x32_bf16 v[10:13], v[114:117], v[118:121], v[98:101]
	v_add_f32_e32 v50, 1.0, v50
	v_div_scale_f32 v51, s[0:1], v50, v50, v53
	v_rcp_f32_e32 v52, v51
	v_mfma_f32_16x16x32_bf16 v[14:17], v[114:117], v[122:125], v[102:105]
	v_fma_f32 v54, -v51, v52, 1.0
	v_fmac_f32_e32 v52, v54, v52
	v_div_scale_f32 v54, vcc, v53, v50, v53
	v_mul_f32_e32 v55, v54, v52
	v_fma_f32 v56, -v51, v55, v54
	v_fmac_f32_e32 v55, v56, v52
	v_fma_f32 v51, -v51, v55, v54
	v_div_fmas_f32 v51, v51, v52, v55
	v_div_fixup_f32 v50, v51, v50, v53
	v_mul_f32_e32 v50, v57, v50
	v_cvt_pk_bf16_f32 v50, v50, s0
	ds_write_b16 v0, v50 offset:464
	v_mul_f32_e32 v50, 0xbfb8aa3b, v42
	v_exp_f32_e32 v50, v50
	v_mfma_f32_16x16x32_bf16 v[2:5], v[114:117], v[126:129], v[106:109]
	v_add_f32_e32 v50, 1.0, v50
	v_div_scale_f32 v51, s[0:1], v50, v50, v42
	v_rcp_f32_e32 v52, v51
	v_mfma_f32_16x16x32_bf16 v[6:9], v[114:117], v[130:133], v[110:113]
	v_fma_f32 v53, -v51, v52, 1.0
	v_fmac_f32_e32 v52, v53, v52
	v_div_scale_f32 v53, vcc, v42, v50, v42
	v_mul_f32_e32 v54, v53, v52
	v_fma_f32 v55, -v51, v54, v53
	v_fmac_f32_e32 v54, v55, v52
	v_fma_f32 v51, -v51, v54, v53
	v_div_fmas_f32 v51, v51, v52, v54
	v_div_fixup_f32 v42, v51, v50, v42
	v_mul_f32_e32 v42, v46, v42
	v_cvt_pk_bf16_f32 v42, v42, s0
	ds_write_b16 v0, v42 offset:2304
	v_mul_f32_e32 v42, 0xbfb8aa3b, v43
	v_exp_f32_e32 v42, v42
	s_nop 0
	v_add_f32_e32 v42, 1.0, v42
	v_div_scale_f32 v46, s[0:1], v42, v42, v43
	v_rcp_f32_e32 v50, v46
	s_nop 0
	v_fma_f32 v51, -v46, v50, 1.0
	v_fmac_f32_e32 v50, v51, v50
	v_div_scale_f32 v51, vcc, v43, v42, v43
	v_mul_f32_e32 v52, v51, v50
	v_fma_f32 v53, -v46, v52, v51
	v_fmac_f32_e32 v52, v53, v50
	v_fma_f32 v46, -v46, v52, v51
	v_div_fmas_f32 v46, v46, v50, v52
	v_div_fixup_f32 v42, v46, v42, v43
	v_mul_f32_e32 v42, v47, v42
	v_cvt_pk_bf16_f32 v42, v42, s0
	ds_write_b16 v0, v42 offset:2448
	v_mul_f32_e32 v42, 0xbfb8aa3b, v44
	v_exp_f32_e32 v42, v42
	s_nop 0
	v_add_f32_e32 v42, 1.0, v42
	v_div_scale_f32 v43, s[0:1], v42, v42, v44
	v_rcp_f32_e32 v46, v43
	s_nop 0
	v_fma_f32 v47, -v43, v46, 1.0
	v_fmac_f32_e32 v46, v47, v46
	v_div_scale_f32 v47, vcc, v44, v42, v44
	v_mul_f32_e32 v50, v47, v46
	v_fma_f32 v51, -v43, v50, v47
	v_fmac_f32_e32 v50, v51, v46
	v_fma_f32 v43, -v43, v50, v47
	v_div_fmas_f32 v43, v43, v46, v50
	v_div_fixup_f32 v42, v43, v42, v44
	v_mul_f32_e32 v42, v48, v42
	v_cvt_pk_bf16_f32 v42, v42, s0
	ds_write_b16 v0, v42 offset:2592
	v_mul_f32_e32 v42, 0xbfb8aa3b, v45
	v_exp_f32_e32 v42, v42
	s_nop 0
	v_add_f32_e32 v42, 1.0, v42
	v_div_scale_f32 v43, s[0:1], v42, v42, v45
	v_rcp_f32_e32 v44, v43
	s_nop 0
	v_fma_f32 v46, -v43, v44, 1.0
	v_fmac_f32_e32 v44, v46, v44
	v_div_scale_f32 v46, vcc, v45, v42, v45
	v_mul_f32_e32 v47, v46, v44
	v_fma_f32 v48, -v43, v47, v46
	v_fmac_f32_e32 v47, v48, v44
	v_fma_f32 v43, -v43, v47, v46
	v_div_fmas_f32 v43, v43, v44, v47
	v_div_fixup_f32 v42, v43, v42, v45
	v_mul_f32_e32 v42, v49, v42
	v_cvt_pk_bf16_f32 v42, v42, s0
	ds_write_b16 v0, v42 offset:2736
	v_mul_f32_e32 v42, 0xbfb8aa3b, v34
	v_exp_f32_e32 v42, v42
	s_nop 0
	v_add_f32_e32 v42, 1.0, v42
	v_div_scale_f32 v43, s[0:1], v42, v42, v34
	v_rcp_f32_e32 v44, v43
	s_nop 0
	v_fma_f32 v45, -v43, v44, 1.0
	v_fmac_f32_e32 v44, v45, v44
	v_div_scale_f32 v45, vcc, v34, v42, v34
	v_mul_f32_e32 v46, v45, v44
	v_fma_f32 v47, -v43, v46, v45
	v_fmac_f32_e32 v46, v47, v44
	v_fma_f32 v43, -v43, v46, v45
	v_div_fmas_f32 v43, v43, v44, v46
	v_div_fixup_f32 v34, v43, v42, v34
	v_mul_f32_e32 v34, v38, v34
	v_cvt_pk_bf16_f32 v34, v34, s0
	ds_write_b16 v0, v34 offset:2336
	v_mul_f32_e32 v34, 0xbfb8aa3b, v35
; __device__ __forceinline__ u16 f2bf(float f) { return (u16)(pack2(f, 0.f) & 0xffffu); }
; __device__ __forceinline__ float silu_f(float x) { return x / (1.f + __expf(-x)); }
; __device__ __forceinline__ void phase_moe_up(const Params& p, int l, bool last, unsigned char* smem) {
;     ...
; #pragma unroll
;       for (int mi = 0; mi < 4; ++mi)
; #pragma unroll
;         for (int n2 = 0; n2 < 2; ++n2)
; #pragma unroll
;           for (int j = 0; j < 4; ++j) {
;             const int m = r0 + mi * 16 + j;
;             const int fl = (c0 >> 6) * 32 + n2 * 16 + (c0 & 15);
;             Ts[m * 72 + fl] = f2bf(silu_f(acc[mi][2 * n2][j]) * acc[mi][2 * n2 + 1][j]);
;           }
	v_exp_f32_e32 v34, v34
	s_nop 0
	v_add_f32_e32 v34, 1.0, v34
	v_div_scale_f32 v38, s[0:1], v34, v34, v35
	v_rcp_f32_e32 v42, v38
	s_nop 0
	v_fma_f32 v43, -v38, v42, 1.0
	v_fmac_f32_e32 v42, v43, v42
	v_div_scale_f32 v43, vcc, v35, v34, v35
	v_mul_f32_e32 v44, v43, v42
	v_fma_f32 v45, -v38, v44, v43
	v_fmac_f32_e32 v44, v45, v42
	v_fma_f32 v38, -v38, v44, v43
	v_div_fmas_f32 v38, v38, v42, v44
	v_div_fixup_f32 v34, v38, v34, v35
	v_mul_f32_e32 v34, v39, v34
	v_cvt_pk_bf16_f32 v34, v34, s0
	ds_write_b16 v0, v34 offset:2480
	v_mul_f32_e32 v34, 0xbfb8aa3b, v36
	v_exp_f32_e32 v34, v34
	s_nop 0
	v_add_f32_e32 v34, 1.0, v34
	v_div_scale_f32 v35, s[0:1], v34, v34, v36
	v_rcp_f32_e32 v38, v35
	s_nop 0
	v_fma_f32 v39, -v35, v38, 1.0
	v_fmac_f32_e32 v38, v39, v38
	v_div_scale_f32 v39, vcc, v36, v34, v36
	v_mul_f32_e32 v42, v39, v38
	v_fma_f32 v43, -v35, v42, v39
	v_fmac_f32_e32 v42, v43, v38
	v_fma_f32 v35, -v35, v42, v39
	v_div_fmas_f32 v35, v35, v38, v42
	v_div_fixup_f32 v34, v35, v34, v36
	v_mul_f32_e32 v34, v40, v34
	v_cvt_pk_bf16_f32 v34, v34, s0
	ds_write_b16 v0, v34 offset:2624
	v_mul_f32_e32 v34, 0xbfb8aa3b, v37
	v_exp_f32_e32 v34, v34
	s_nop 0
	v_add_f32_e32 v34, 1.0, v34
	v_div_scale_f32 v35, s[0:1], v34, v34, v37
	v_rcp_f32_e32 v36, v35
	s_nop 0
	v_fma_f32 v38, -v35, v36, 1.0
	v_fmac_f32_e32 v36, v38, v36
	v_div_scale_f32 v38, vcc, v37, v34, v37
	v_mul_f32_e32 v39, v38, v36
	v_fma_f32 v40, -v35, v39, v38
	v_fmac_f32_e32 v39, v40, v36
	v_fma_f32 v35, -v35, v39, v38
	v_div_fmas_f32 v35, v35, v36, v39
	v_div_fixup_f32 v34, v35, v34, v37
	v_mul_f32_e32 v34, v41, v34
	v_cvt_pk_bf16_f32 v34, v34, s0
	ds_write_b16 v0, v34 offset:2768
	v_mul_f32_e32 v34, 0xbfb8aa3b, v26
	v_exp_f32_e32 v34, v34
	s_nop 0
	v_add_f32_e32 v34, 1.0, v34
	v_div_scale_f32 v35, s[0:1], v34, v34, v26
	v_rcp_f32_e32 v36, v35
	s_nop 0
	v_fma_f32 v37, -v35, v36, 1.0
	v_fmac_f32_e32 v36, v37, v36
	v_div_scale_f32 v37, vcc, v26, v34, v26
	v_mul_f32_e32 v38, v37, v36
	v_fma_f32 v39, -v35, v38, v37
	v_fmac_f32_e32 v38, v39, v36
	v_fma_f32 v35, -v35, v38, v37
	v_div_fmas_f32 v35, v35, v36, v38
	v_div_fixup_f32 v26, v35, v34, v26
	v_mul_f32_e32 v26, v30, v26
	v_cvt_pk_bf16_f32 v26, v26, s0
	ds_write_b16 v0, v26 offset:4608
	v_mul_f32_e32 v26, 0xbfb8aa3b, v27
	v_exp_f32_e32 v26, v26
	s_nop 0
	v_add_f32_e32 v26, 1.0, v26
	v_div_scale_f32 v30, s[0:1], v26, v26, v27
	v_rcp_f32_e32 v34, v30
	s_nop 0
	v_fma_f32 v35, -v30, v34, 1.0
	v_fmac_f32_e32 v34, v35, v34
	v_div_scale_f32 v35, vcc, v27, v26, v27
	v_mul_f32_e32 v36, v35, v34
	v_fma_f32 v37, -v30, v36, v35
	v_fmac_f32_e32 v36, v37, v34
	v_fma_f32 v30, -v30, v36, v35
	v_div_fmas_f32 v30, v30, v34, v36
	v_div_fixup_f32 v26, v30, v26, v27
	v_mul_f32_e32 v26, v31, v26
	v_cvt_pk_bf16_f32 v26, v26, s0
	ds_write_b16 v0, v26 offset:4752
	v_mul_f32_e32 v26, 0xbfb8aa3b, v28
	v_exp_f32_e32 v26, v26
	s_nop 0
	v_add_f32_e32 v26, 1.0, v26
	v_div_scale_f32 v27, s[0:1], v26, v26, v28
	v_rcp_f32_e32 v30, v27
	s_nop 0
	v_fma_f32 v31, -v27, v30, 1.0
	v_fmac_f32_e32 v30, v31, v30
	v_div_scale_f32 v31, vcc, v28, v26, v28
	v_mul_f32_e32 v34, v31, v30
	v_fma_f32 v35, -v27, v34, v31
	v_fmac_f32_e32 v34, v35, v30
	v_fma_f32 v27, -v27, v34, v31
	v_div_fmas_f32 v27, v27, v30, v34
	v_div_fixup_f32 v26, v27, v26, v28
	v_mul_f32_e32 v26, v32, v26
	v_cvt_pk_bf16_f32 v26, v26, s0
	ds_write_b16 v0, v26 offset:4896
	v_mul_f32_e32 v26, 0xbfb8aa3b, v29
	v_exp_f32_e32 v26, v26
	s_nop 0
	v_add_f32_e32 v26, 1.0, v26
	v_div_scale_f32 v27, s[0:1], v26, v26, v29
	v_rcp_f32_e32 v28, v27
	s_nop 0
	v_fma_f32 v30, -v27, v28, 1.0
	v_fmac_f32_e32 v28, v30, v28
	v_div_scale_f32 v30, vcc, v29, v26, v29
	v_mul_f32_e32 v31, v30, v28
	v_fma_f32 v32, -v27, v31, v30
	v_fmac_f32_e32 v31, v32, v28
	v_fma_f32 v27, -v27, v31, v30
	v_div_fmas_f32 v27, v27, v28, v31
	v_div_fixup_f32 v26, v27, v26, v29
	v_mul_f32_e32 v26, v33, v26
	v_cvt_pk_bf16_f32 v26, v26, s0
	ds_write_b16 v0, v26 offset:5040
	v_mul_f32_e32 v26, 0xbfb8aa3b, v18
	v_exp_f32_e32 v26, v26
	s_nop 0
	v_add_f32_e32 v26, 1.0, v26
	v_div_scale_f32 v27, s[0:1], v26, v26, v18
	v_rcp_f32_e32 v28, v27
	s_nop 0
	v_fma_f32 v29, -v27, v28, 1.0
	v_fmac_f32_e32 v28, v29, v28
	v_div_scale_f32 v29, vcc, v18, v26, v18
	v_mul_f32_e32 v30, v29, v28
	v_fma_f32 v31, -v27, v30, v29
	v_fmac_f32_e32 v30, v31, v28
	v_fma_f32 v27, -v27, v30, v29
	v_div_fmas_f32 v27, v27, v28, v30
	v_div_fixup_f32 v18, v27, v26, v18
	v_mul_f32_e32 v18, v22, v18
	v_cvt_pk_bf16_f32 v18, v18, s0
	ds_write_b16 v0, v18 offset:4640
	v_mul_f32_e32 v18, 0xbfb8aa3b, v19
	v_exp_f32_e32 v18, v18
	s_nop 0
	v_add_f32_e32 v18, 1.0, v18
	v_div_scale_f32 v22, s[0:1], v18, v18, v19
	v_rcp_f32_e32 v26, v22
	s_nop 0
	v_fma_f32 v27, -v22, v26, 1.0
	v_fmac_f32_e32 v26, v27, v26
	v_div_scale_f32 v27, vcc, v19, v18, v19
	v_mul_f32_e32 v28, v27, v26
	v_fma_f32 v29, -v22, v28, v27
	v_fmac_f32_e32 v28, v29, v26
	v_fma_f32 v22, -v22, v28, v27
	v_div_fmas_f32 v22, v22, v26, v28
	v_div_fixup_f32 v18, v22, v18, v19
	v_mul_f32_e32 v18, v23, v18
	v_cvt_pk_bf16_f32 v18, v18, s0
	ds_write_b16 v0, v18 offset:4784
	v_mul_f32_e32 v18, 0xbfb8aa3b, v20
	v_exp_f32_e32 v18, v18
	s_nop 0
	v_add_f32_e32 v18, 1.0, v18
	v_div_scale_f32 v19, s[0:1], v18, v18, v20
	v_rcp_f32_e32 v22, v19
	s_nop 0
	v_fma_f32 v23, -v19, v22, 1.0
	v_fmac_f32_e32 v22, v23, v22
	v_div_scale_f32 v23, vcc, v20, v18, v20
	v_mul_f32_e32 v26, v23, v22
	v_fma_f32 v27, -v19, v26, v23
	v_fmac_f32_e32 v26, v27, v22
	v_fma_f32 v19, -v19, v26, v23
	v_div_fmas_f32 v19, v19, v22, v26
	v_div_fixup_f32 v18, v19, v18, v20
	v_mul_f32_e32 v18, v24, v18
	v_cvt_pk_bf16_f32 v18, v18, s0
	ds_write_b16 v0, v18 offset:4928
	v_mul_f32_e32 v18, 0xbfb8aa3b, v21
; __device__ __forceinline__ u16 f2bf(float f) { return (u16)(pack2(f, 0.f) & 0xffffu); }
; __device__ __forceinline__ float silu_f(float x) { return x / (1.f + __expf(-x)); }
; __device__ __forceinline__ void phase_moe_up(const Params& p, int l, bool last, unsigned char* smem) {
;     ...
;           for (int j = 0; j < 4; ++j) {
;             const int m = r0 + mi * 16 + j;
;             const int fl = (c0 >> 6) * 32 + n2 * 16 + (c0 & 15);
;             Ts[m * 72 + fl] = f2bf(silu_f(acc[mi][2 * n2][j]) * acc[mi][2 * n2 + 1][j]);
;           }
;       __syncthreads();
; #pragma unroll
;       for (int i = 0; i < 4; ++i) {
;         const int c = t2 + 256 * i, row = c >> 3, ch = c & 7;
;         if (row < mvalid) *(u32x4*)(p.HID + (size_t)(hid_row + row) * 512 + nt * 64 + ch * 8) = *(const u32x4*)(Ts + row * 72 + ch * 8);
	v_exp_f32_e32 v18, v18
	s_nop 0
	v_add_f32_e32 v18, 1.0, v18
	v_div_scale_f32 v19, s[0:1], v18, v18, v21
	v_rcp_f32_e32 v20, v19
	s_nop 0
	v_fma_f32 v22, -v19, v20, 1.0
	v_fmac_f32_e32 v20, v22, v20
	v_div_scale_f32 v22, vcc, v21, v18, v21
	v_mul_f32_e32 v23, v22, v20
	v_fma_f32 v24, -v19, v23, v22
	v_fmac_f32_e32 v23, v24, v20
	v_fma_f32 v19, -v19, v23, v22
	v_div_fmas_f32 v19, v19, v20, v23
	v_div_fixup_f32 v18, v19, v18, v21
	v_mul_f32_e32 v18, v25, v18
	v_cvt_pk_bf16_f32 v18, v18, s0
	ds_write_b16 v0, v18 offset:5072
	v_mul_f32_e32 v18, 0xbfb8aa3b, v10
	v_exp_f32_e32 v18, v18
	s_nop 0
	v_add_f32_e32 v18, 1.0, v18
	v_div_scale_f32 v19, s[0:1], v18, v18, v10
	v_rcp_f32_e32 v20, v19
	s_nop 0
	v_fma_f32 v21, -v19, v20, 1.0
	v_fmac_f32_e32 v20, v21, v20
	v_div_scale_f32 v21, vcc, v10, v18, v10
	v_mul_f32_e32 v22, v21, v20
	v_fma_f32 v23, -v19, v22, v21
	v_fmac_f32_e32 v22, v23, v20
	v_fma_f32 v19, -v19, v22, v21
	v_div_fmas_f32 v19, v19, v20, v22
	v_div_fixup_f32 v10, v19, v18, v10
	v_mul_f32_e32 v10, v14, v10
	v_cvt_pk_bf16_f32 v10, v10, s0
	ds_write_b16 v0, v10 offset:6912
	v_mul_f32_e32 v10, 0xbfb8aa3b, v11
	v_exp_f32_e32 v10, v10
	s_nop 0
	v_add_f32_e32 v10, 1.0, v10
	v_div_scale_f32 v14, s[0:1], v10, v10, v11
	v_rcp_f32_e32 v18, v14
	s_nop 0
	v_fma_f32 v19, -v14, v18, 1.0
	v_fmac_f32_e32 v18, v19, v18
	v_div_scale_f32 v19, vcc, v11, v10, v11
	v_mul_f32_e32 v20, v19, v18
	v_fma_f32 v21, -v14, v20, v19
	v_fmac_f32_e32 v20, v21, v18
	v_fma_f32 v14, -v14, v20, v19
	v_div_fmas_f32 v14, v14, v18, v20
	v_div_fixup_f32 v10, v14, v10, v11
	v_mul_f32_e32 v10, v15, v10
	v_cvt_pk_bf16_f32 v10, v10, s0
	ds_write_b16 v0, v10 offset:7056
	v_mul_f32_e32 v10, 0xbfb8aa3b, v12
	v_exp_f32_e32 v10, v10
	s_nop 0
	v_add_f32_e32 v10, 1.0, v10
	v_div_scale_f32 v11, s[0:1], v10, v10, v12
	v_rcp_f32_e32 v14, v11
	s_nop 0
	v_fma_f32 v15, -v11, v14, 1.0
	v_fmac_f32_e32 v14, v15, v14
	v_div_scale_f32 v15, vcc, v12, v10, v12
	v_mul_f32_e32 v18, v15, v14
	v_fma_f32 v19, -v11, v18, v15
	v_fmac_f32_e32 v18, v19, v14
	v_fma_f32 v11, -v11, v18, v15
	v_div_fmas_f32 v11, v11, v14, v18
	v_div_fixup_f32 v10, v11, v10, v12
	v_mul_f32_e32 v10, v16, v10
	v_cvt_pk_bf16_f32 v10, v10, s0
	ds_write_b16 v0, v10 offset:7200
	v_mul_f32_e32 v10, 0xbfb8aa3b, v13
	v_exp_f32_e32 v10, v10
	s_nop 0
	v_add_f32_e32 v10, 1.0, v10
	v_div_scale_f32 v11, s[0:1], v10, v10, v13
	v_rcp_f32_e32 v12, v11
	s_nop 0
	v_fma_f32 v14, -v11, v12, 1.0
	v_fmac_f32_e32 v12, v14, v12
	v_div_scale_f32 v14, vcc, v13, v10, v13
	v_mul_f32_e32 v15, v14, v12
	v_fma_f32 v16, -v11, v15, v14
	v_fmac_f32_e32 v15, v16, v12
	v_fma_f32 v11, -v11, v15, v14
	v_div_fmas_f32 v11, v11, v12, v15
	v_div_fixup_f32 v10, v11, v10, v13
	v_mul_f32_e32 v10, v17, v10
	v_cvt_pk_bf16_f32 v10, v10, s0
	ds_write_b16 v0, v10 offset:7344
	v_mul_f32_e32 v10, 0xbfb8aa3b, v2
	v_exp_f32_e32 v10, v10
	s_nop 0
	v_add_f32_e32 v10, 1.0, v10
	v_div_scale_f32 v11, s[0:1], v10, v10, v2
	v_rcp_f32_e32 v12, v11
	s_nop 0
	v_fma_f32 v13, -v11, v12, 1.0
	v_fmac_f32_e32 v12, v13, v12
	v_div_scale_f32 v13, vcc, v2, v10, v2
	v_mul_f32_e32 v14, v13, v12
	v_fma_f32 v15, -v11, v14, v13
	v_fmac_f32_e32 v14, v15, v12
	v_fma_f32 v11, -v11, v14, v13
	v_div_fmas_f32 v11, v11, v12, v14
	v_div_fixup_f32 v2, v11, v10, v2
	v_mul_f32_e32 v2, v6, v2
	v_cvt_pk_bf16_f32 v2, v2, s0
	ds_write_b16 v0, v2 offset:6944
	v_mul_f32_e32 v2, 0xbfb8aa3b, v3
	v_exp_f32_e32 v2, v2
	s_nop 0
	v_add_f32_e32 v2, 1.0, v2
	v_div_scale_f32 v6, s[0:1], v2, v2, v3
	v_rcp_f32_e32 v10, v6
	s_nop 0
	v_fma_f32 v11, -v6, v10, 1.0
	v_fmac_f32_e32 v10, v11, v10
	v_div_scale_f32 v11, vcc, v3, v2, v3
	v_mul_f32_e32 v12, v11, v10
	v_fma_f32 v13, -v6, v12, v11
	v_fmac_f32_e32 v12, v13, v10
	v_fma_f32 v6, -v6, v12, v11
	v_div_fmas_f32 v6, v6, v10, v12
	v_div_fixup_f32 v2, v6, v2, v3
	v_mul_f32_e32 v2, v7, v2
	v_cvt_pk_bf16_f32 v2, v2, s0
	ds_write_b16 v0, v2 offset:7088
	v_mul_f32_e32 v2, 0xbfb8aa3b, v4
	v_exp_f32_e32 v2, v2
	s_nop 0
	v_add_f32_e32 v2, 1.0, v2
	v_div_scale_f32 v3, s[0:1], v2, v2, v4
	v_rcp_f32_e32 v6, v3
	s_nop 0
	v_fma_f32 v7, -v3, v6, 1.0
	v_fmac_f32_e32 v6, v7, v6
	v_div_scale_f32 v7, vcc, v4, v2, v4
	v_mul_f32_e32 v10, v7, v6
	v_fma_f32 v11, -v3, v10, v7
	v_fmac_f32_e32 v10, v11, v6
	v_fma_f32 v3, -v3, v10, v7
	v_div_fmas_f32 v3, v3, v6, v10
	v_div_fixup_f32 v2, v3, v2, v4
	v_mul_f32_e32 v2, v8, v2
	v_cvt_pk_bf16_f32 v2, v2, s0
	ds_write_b16 v0, v2 offset:7232
	v_mul_f32_e32 v2, 0xbfb8aa3b, v5
	v_exp_f32_e32 v2, v2
	s_nop 0
	v_add_f32_e32 v2, 1.0, v2
	v_div_scale_f32 v3, s[0:1], v2, v2, v5
	v_rcp_f32_e32 v4, v3
	s_nop 0
	v_fma_f32 v6, -v3, v4, 1.0
	v_fmac_f32_e32 v4, v6, v4
	v_div_scale_f32 v6, vcc, v5, v2, v5
	v_mul_f32_e32 v7, v6, v4
	v_fma_f32 v8, -v3, v7, v6
	v_fmac_f32_e32 v7, v8, v4
	v_fma_f32 v3, -v3, v7, v6
	v_div_fmas_f32 v3, v3, v4, v7
	v_div_fixup_f32 v2, v3, v2, v5
	v_mul_f32_e32 v2, v9, v2
	v_cvt_pk_bf16_f32 v2, v2, s0
	ds_write_b16 v0, v2 offset:7376
	v_lshlrev_b32_e32 v0, 3, v66
	v_and_b32_e32 v0, 56, v0
	v_ashrrev_i32_e32 v3, 3, v66
	v_lshlrev_b32_e32 v2, 1, v0
	v_cmp_gt_i32_e32 vcc, s86, v3
	s_waitcnt lgkmcnt(0)
	s_barrier
	s_and_saveexec_b64 s[0:1], vcc
	s_cbranch_execz .LBB0_1165
	v_mov_b64_e32 v[4:5], s[4:5]
	s_load_dwordx2 s[100:101], s[4:5], 0x170
	s_waitcnt lgkmcnt(0)
	v_mov_b32_e32 v8, s100
	v_mov_b32_e32 v9, s101
	v_mad_u64_u32 v[4:5], s[8:9], v3, s96, v[2:3]
	v_add_u32_e32 v10, s82, v3
	ds_read_b128 v[4:7], v4
	v_ashrrev_i32_e32 v11, 31, v10
	v_lshlrev_b64 v[10:11], 10, v[10:11]
	s_lshl_b32 s94, s83, 7
	v_mov_b32_e32 v3, v1
	s_waitcnt lgkmcnt(0)
	v_lshl_add_u64 v[8:9], v[8:9], 0, v[10:11]
	v_lshl_add_u64 v[8:9], v[8:9], 0, s[94:95]
	v_lshl_add_u64 v[8:9], v[8:9], 0, v[2:3]
	global_store_dwordx4 v[8:9], v[4:7], off
